# code placement: also 64-byte align attention inner loop heads (xattn PV/DMA loops, DIL DMA loops, S5-out loop)
# baseline (speedup 1.0000x reference)
; #define LAS __attribute__((address_space(3)))
; __device__ __forceinline__ void glds16(const void* gsrc, LAS unsigned char* dst_uniform) { __builtin_amdgcn_global_load_lds((const unsigned*)gsrc, (LAS unsigned*)dst_uniform, 16, 0, 0); }
; #define ATT_SYNC() do { asm volatile("s_waitcnt vmcnt(0) lgkmcnt(0)" ::: "memory"); __syncthreads(); } while (0)
; __device__ __forceinline__ void xattn_unit(LAS unsigned char* lds, const bf16_t* Qx, const bf16_t* KV, int li, int b, int h, int qb, bf16_t* XO, const int tid) {
;     const int lane = tid & 63, wid = __builtin_amdgcn_readfirstlane(tid >> 6), r32 = lane & 31, hi = lane >> 5;
;     const size_t tok = (size_t)b * SEQ + qb * 256 + wid * 32 + r32;
;     const bf16_t* Kb = KV + (size_t)b * MEMLEN * 8192 + li * 2048 + h * 256;
; #pragma unroll 4
;     for (int ii = 0; ii < 16; ++ii) { const int i = wid * 16 + ii, key = 2 * i + hi, c = r32 ^ (key & 15);
;         glds16(Kb + (size_t)key * 8192 + c * 8, lds + i * 1024); }
;     bf16x8 qf[16]; { const bf16_t* qp = Qx + tok * 1024 + h * 256 + hi * 8;
; #pragma unroll
;         for (int s = 0; s < 16; ++s) qf[s] = *(const bf16x8*)(qp + 16 * s); }
;     ATT_SYNC();
;     f32x16 S[8];
; #pragma unroll
;     for (int kt = 0; kt < 8; ++kt) { f32x16 acc = {}; const lds_cptr kp = (lds_cptr)lds + (32 * kt + r32) * 512;
; #pragma unroll
;         for (int s = 0; s < 16; ++s) { const bf16x8 kf = *(const LAS bf16x8*)(kp + (((2 * s + hi) ^ (r32 & 15)) << 4)); acc = __builtin_amdgcn_mfma_f32_32x32x16_bf16(kf, qf[s], acc, 0, 0, 0); }
;         S[kt] = acc; }
.LBB0_431:
	v_readfirstlane_b32 s1, v202
	s_ashr_i32 s25, s1, 6
	s_lshl_b32 s36, s25, 5
	v_or_b32_e32 v0, 6, v204
	v_or_b32_e32 v0, s36, v0
	v_readlane_b32 s30, v254, 36
	v_readlane_b32 s12, v254, 35
	v_ashrrev_i32_e32 v1, 31, v0
	s_ashr_i32 s0, s30, 4
	s_lshl_b32 s12, s12, 8
	v_lshlrev_b64 v[2:3], 14, v[0:1]
	v_or_b32_e32 v1, 4, v204
	s_ashr_i32 s1, s0, 31
	s_ashr_i32 s13, s12, 31
	s_lshl_b32 s18, s25, 14
	v_or_b32_e32 v4, s36, v1
	v_or_b32_e32 v1, 2, v204
	s_lshl_b64 s[14:15], s[0:1], 22
	s_add_i32 s24, s18, 0
	s_lshl_b64 s[18:19], s[12:13], 1
	v_or_b32_e32 v6, s36, v1
	v_or_b32_e32 v8, s36, v204
	s_add_u32 s26, s20, s14
	v_ashrrev_i32_e32 v5, 31, v4
	v_ashrrev_i32_e32 v7, 31, v6
	v_ashrrev_i32_e32 v9, 31, v8
	s_addc_u32 s27, s21, s15
	v_lshlrev_b64 v[4:5], 14, v[4:5]
	v_lshlrev_b64 v[6:7], 14, v[6:7]
	v_lshlrev_b64 v[8:9], 14, v[8:9]
	v_lshl_add_u64 v[2:3], s[26:27], 0, v[2:3]
	v_lshl_add_u64 v[4:5], s[26:27], 0, v[4:5]
	v_lshl_add_u64 v[6:7], s[26:27], 0, v[6:7]
	v_lshl_add_u64 v[8:9], s[26:27], 0, v[8:9]
	s_mov_b32 s25, 0
	s_mov_b64 s[28:29], 0x20000
	.p2alignl 6, 3212836864
.LBB0_432:
	v_add_u32_e32 v1, -6, v0
	v_bitop3_b32 v1, v1, v203, 9 bitop3:0x6c
	v_lshlrev_b32_e32 v208, 4, v1
	v_lshl_add_u64 v[10:11], v[8:9], 0, s[18:19]
	s_add_i32 s26, s24, s25
	v_add_u32_e32 v1, -4, v0
	v_lshl_add_u64 v[10:11], v[10:11], 0, v[208:209]
	s_mov_b32 m0, s26
	v_bitop3_b32 v1, v1, v203, 11 bitop3:0x6c
	global_load_lds_dwordx4 v[10:11], off
	v_lshlrev_b32_e32 v208, 4, v1
	v_lshl_add_u64 v[10:11], v[6:7], 0, s[18:19]
	v_add_u32_e32 v1, -2, v0
	v_lshl_add_u64 v[10:11], v[10:11], 0, v[208:209]
	s_add_i32 m0, s26, 0x400
	v_bitop3_b32 v1, v1, v203, 13 bitop3:0x6c
	global_load_lds_dwordx4 v[10:11], off
	v_lshlrev_b32_e32 v208, 4, v1
	v_lshl_add_u64 v[10:11], v[4:5], 0, s[18:19]
	v_lshl_add_u64 v[10:11], v[10:11], 0, v[208:209]
	s_add_i32 m0, s26, 0x800
	v_bitop3_b32 v1, v0, v203, 15 bitop3:0x6c
	global_load_lds_dwordx4 v[10:11], off
	v_lshlrev_b32_e32 v208, 4, v1
	v_lshl_add_u64 v[10:11], v[2:3], 0, s[18:19]
	v_lshl_add_u64 v[10:11], v[10:11], 0, v[208:209]
	s_add_i32 m0, s26, 0xc00
	s_addk_i32 s25, 0x1000
	global_load_lds_dwordx4 v[10:11], off
	v_lshl_add_u64 v[2:3], v[2:3], 0, s[28:29]
	v_add_u32_e32 v0, 8, v0
	v_lshl_add_u64 v[4:5], v[4:5], 0, s[28:29]
	v_lshl_add_u64 v[6:7], v[6:7], 0, s[28:29]
	v_lshl_add_u64 v[8:9], v[8:9], 0, s[28:29]
	s_cmpk_eq_i32 s25, 0x4000
	s_cbranch_scc0 .LBB0_432
	s_lshl_b32 s25, s30, 8
	s_and_b32 s25, s25, 0xf00
	s_lshl_b64 s[0:1], s[0:1], 12
	v_or_b32_e32 v0, s25, v203
	s_ashr_i32 s37, s36, 31
	v_or_b32_e32 v0, s0, v0
	v_mov_b32_e32 v1, s1
	v_lshl_add_u64 v[0:1], v[0:1], 0, s[36:37]
	v_lshlrev_b64 v[200:201], 10, v[0:1]
	v_lshlrev_b64 v[0:1], 11, v[0:1]
	v_lshl_add_u64 v[0:1], s[8:9], 0, v[0:1]
	v_lshl_add_u64 v[0:1], s[12:13], 1, v[0:1]
	v_mov_b32_e32 v197, v209
	v_lshl_add_u64 v[0:1], v[0:1], 0, v[196:197]
	global_load_dwordx4 v[112:115], v[0:1], off
	global_load_dwordx4 v[184:187], v[0:1], off offset:32
	global_load_dwordx4 v[180:183], v[0:1], off offset:64
	global_load_dwordx4 v[176:179], v[0:1], off offset:96
	global_load_dwordx4 v[172:175], v[0:1], off offset:128
	global_load_dwordx4 v[168:171], v[0:1], off offset:160
	global_load_dwordx4 v[164:167], v[0:1], off offset:192
	global_load_dwordx4 v[160:163], v[0:1], off offset:224
	global_load_dwordx4 v[156:159], v[0:1], off offset:256
	global_load_dwordx4 v[152:155], v[0:1], off offset:288
	global_load_dwordx4 v[148:151], v[0:1], off offset:320
	global_load_dwordx4 v[144:147], v[0:1], off offset:352
	global_load_dwordx4 v[140:143], v[0:1], off offset:384
	global_load_dwordx4 v[136:139], v[0:1], off offset:416
	global_load_dwordx4 v[132:135], v[0:1], off offset:448
	global_load_dwordx4 v[128:131], v[0:1], off offset:480
	v_add_u32_e32 v32, v205, v206
	s_waitcnt vmcnt(0) lgkmcnt(0)
	s_waitcnt vmcnt(0) lgkmcnt(0)
	s_barrier
	ds_read_b128 v[0:3], v32
	v_add_u32_e32 v78, v205, v207
	ds_read_b128 v[16:19], v78
	v_add_u32_e32 v77, v205, v211
	v_add_u32_e32 v76, v205, v212
	v_add_u32_e32 v75, v205, v218
	v_add_u32_e32 v74, v205, v219
	v_add_u32_e32 v73, v205, v220
	v_add_u32_e32 v72, v205, v221
	v_add_u32_e32 v71, v205, v237
	v_add_u32_e32 v70, v205, v238
	v_add_u32_e32 v69, v205, v239
	v_add_u32_e32 v68, v205, v240
	v_add_u32_e32 v67, v205, v241
	v_add_u32_e32 v66, v205, v242
	v_add_u32_e32 v65, v205, v243
	v_add_u32_e32 v64, v205, v244
	v_add_u32_e32 v197, v248, v207
	v_add_u32_e32 v96, v246, v207
	v_add_u32_e32 v116, v247, v207
	s_add_u32 s14, s14, s18
	s_addc_u32 s15, s15, s19
	s_lshl_b64 s[0:1], s[36:37], 1
	s_add_u32 s0, s14, s0
	s_addc_u32 s1, s15, s1
	s_waitcnt lgkmcnt(1)
	v_mfma_f32_32x32x16_bf16 v[0:15], v[0:3], v[112:115], 0
	ds_read_b128 v[222:225], v197
	ds_read_b128 v[34:37], v78 offset:16384
	ds_read_b128 v[96:99], v96
	ds_read_b128 v[116:119], v116
	s_waitcnt lgkmcnt(4)
	v_mfma_f32_32x32x16_bf16 v[0:15], v[16:19], v[184:187], v[0:15]
	ds_read_b128 v[16:19], v77
	s_waitcnt lgkmcnt(0)
	v_mfma_f32_32x32x16_bf16 v[0:15], v[16:19], v[180:183], v[0:15]
	ds_read_b128 v[16:19], v76
	s_waitcnt lgkmcnt(0)
	v_mfma_f32_32x32x16_bf16 v[0:15], v[16:19], v[176:179], v[0:15]
	ds_read_b128 v[16:19], v75
	s_waitcnt lgkmcnt(0)
	v_mfma_f32_32x32x16_bf16 v[0:15], v[16:19], v[172:175], v[0:15]
	ds_read_b128 v[16:19], v74
	s_waitcnt lgkmcnt(0)
	v_mfma_f32_32x32x16_bf16 v[0:15], v[16:19], v[168:171], v[0:15]
	ds_read_b128 v[16:19], v73
	s_waitcnt lgkmcnt(0)
	v_mfma_f32_32x32x16_bf16 v[0:15], v[16:19], v[164:167], v[0:15]
	ds_read_b128 v[16:19], v72
	s_waitcnt lgkmcnt(0)
	v_mfma_f32_32x32x16_bf16 v[0:15], v[16:19], v[160:163], v[0:15]
	ds_read_b128 v[16:19], v71
	s_waitcnt lgkmcnt(0)
; #define LAS __attribute__((address_space(3)))
; __device__ __forceinline__ void xattn_unit(LAS unsigned char* lds, const bf16_t* Qx, const bf16_t* KV, int li, int b, int h, int qb, bf16_t* XO, const int tid) {
;     ...
;     for (int kt = 0; kt < 8; ++kt) { f32x16 acc = {}; const lds_cptr kp = (lds_cptr)lds + (32 * kt + r32) * 512;
; #pragma unroll
;         for (int s = 0; s < 16; ++s) { const bf16x8 kf = *(const LAS bf16x8*)(kp + (((2 * s + hi) ^ (r32 & 15)) << 4)); acc = __builtin_amdgcn_mfma_f32_32x32x16_bf16(kf, qf[s], acc, 0, 0, 0); }
;         S[kt] = acc; }
	v_mfma_f32_32x32x16_bf16 v[0:15], v[16:19], v[156:159], v[0:15]
	ds_read_b128 v[16:19], v70
	s_waitcnt lgkmcnt(0)
	v_mfma_f32_32x32x16_bf16 v[0:15], v[16:19], v[152:155], v[0:15]
	ds_read_b128 v[16:19], v69
	s_waitcnt lgkmcnt(0)
	v_mfma_f32_32x32x16_bf16 v[0:15], v[16:19], v[148:151], v[0:15]
	ds_read_b128 v[16:19], v68
	s_waitcnt lgkmcnt(0)
	v_mfma_f32_32x32x16_bf16 v[0:15], v[16:19], v[144:147], v[0:15]
	ds_read_b128 v[16:19], v67
	s_waitcnt lgkmcnt(0)
	v_mfma_f32_32x32x16_bf16 v[0:15], v[16:19], v[140:143], v[0:15]
	ds_read_b128 v[16:19], v66
	s_waitcnt lgkmcnt(0)
	v_mfma_f32_32x32x16_bf16 v[0:15], v[16:19], v[136:139], v[0:15]
	ds_read_b128 v[16:19], v65
	s_waitcnt lgkmcnt(0)
	v_mfma_f32_32x32x16_bf16 v[0:15], v[16:19], v[132:135], v[0:15]
	ds_read_b128 v[16:19], v64
	s_waitcnt lgkmcnt(0)
	v_mfma_f32_32x32x16_bf16 v[0:15], v[16:19], v[128:131], v[0:15]
	ds_read_b128 v[16:19], v32 offset:16384
	s_waitcnt lgkmcnt(0)
	v_mfma_f32_32x32x16_bf16 v[16:31], v[16:19], v[112:115], 0
	v_mfma_f32_32x32x16_bf16 v[16:31], v[34:37], v[184:187], v[16:31]
	ds_read_b128 v[34:37], v77 offset:16384
	s_waitcnt lgkmcnt(0)
	v_mfma_f32_32x32x16_bf16 v[16:31], v[34:37], v[180:183], v[16:31]
	ds_read_b128 v[34:37], v76 offset:16384
	s_waitcnt lgkmcnt(0)
	v_mfma_f32_32x32x16_bf16 v[16:31], v[34:37], v[176:179], v[16:31]
	ds_read_b128 v[34:37], v75 offset:16384
	s_waitcnt lgkmcnt(0)
	v_mfma_f32_32x32x16_bf16 v[16:31], v[34:37], v[172:175], v[16:31]
	ds_read_b128 v[34:37], v74 offset:16384
	s_waitcnt lgkmcnt(0)
	v_mfma_f32_32x32x16_bf16 v[16:31], v[34:37], v[168:171], v[16:31]
	ds_read_b128 v[34:37], v73 offset:16384
	s_waitcnt lgkmcnt(0)
	v_mfma_f32_32x32x16_bf16 v[16:31], v[34:37], v[164:167], v[16:31]
	ds_read_b128 v[34:37], v72 offset:16384
	s_waitcnt lgkmcnt(0)
	v_mfma_f32_32x32x16_bf16 v[16:31], v[34:37], v[160:163], v[16:31]
	ds_read_b128 v[34:37], v71 offset:16384
	s_waitcnt lgkmcnt(0)
	v_mfma_f32_32x32x16_bf16 v[16:31], v[34:37], v[156:159], v[16:31]
	ds_read_b128 v[34:37], v70 offset:16384
	s_waitcnt lgkmcnt(0)
	v_mfma_f32_32x32x16_bf16 v[16:31], v[34:37], v[152:155], v[16:31]
	ds_read_b128 v[34:37], v69 offset:16384
	s_waitcnt lgkmcnt(0)
	v_mfma_f32_32x32x16_bf16 v[16:31], v[34:37], v[148:151], v[16:31]
	ds_read_b128 v[34:37], v68 offset:16384
	s_waitcnt lgkmcnt(0)
	v_mfma_f32_32x32x16_bf16 v[16:31], v[34:37], v[144:147], v[16:31]
	ds_read_b128 v[34:37], v67 offset:16384
	s_waitcnt lgkmcnt(0)
	v_mfma_f32_32x32x16_bf16 v[16:31], v[34:37], v[140:143], v[16:31]
	ds_read_b128 v[34:37], v66 offset:16384
	s_waitcnt lgkmcnt(0)
	v_mfma_f32_32x32x16_bf16 v[16:31], v[34:37], v[136:139], v[16:31]
	ds_read_b128 v[34:37], v65 offset:16384
	s_waitcnt lgkmcnt(0)
	v_mfma_f32_32x32x16_bf16 v[16:31], v[34:37], v[132:135], v[16:31]
	ds_read_b128 v[34:37], v64 offset:16384
	s_waitcnt lgkmcnt(0)
	v_mfma_f32_32x32x16_bf16 v[16:31], v[34:37], v[128:131], v[16:31]
	ds_read_b128 v[34:37], v32 offset:32768
	s_waitcnt lgkmcnt(0)
	v_mfma_f32_32x32x16_bf16 v[48:63], v[34:37], v[112:115], 0
	ds_read_b128 v[34:37], v78 offset:32768
	ds_read_b128 v[78:81], v78 offset:49152
	s_waitcnt lgkmcnt(1)
	v_mfma_f32_32x32x16_bf16 v[48:63], v[34:37], v[184:187], v[48:63]
	ds_read_b128 v[34:37], v77 offset:32768
	s_waitcnt lgkmcnt(0)
	v_mfma_f32_32x32x16_bf16 v[48:63], v[34:37], v[180:183], v[48:63]
	ds_read_b128 v[34:37], v76 offset:32768
	s_waitcnt lgkmcnt(0)
	v_mfma_f32_32x32x16_bf16 v[48:63], v[34:37], v[176:179], v[48:63]
	ds_read_b128 v[34:37], v75 offset:32768
	s_waitcnt lgkmcnt(0)
	v_mfma_f32_32x32x16_bf16 v[48:63], v[34:37], v[172:175], v[48:63]
	ds_read_b128 v[34:37], v74 offset:32768
	s_waitcnt lgkmcnt(0)
	v_mfma_f32_32x32x16_bf16 v[48:63], v[34:37], v[168:171], v[48:63]
	ds_read_b128 v[34:37], v73 offset:32768
	s_waitcnt lgkmcnt(0)
	v_mfma_f32_32x32x16_bf16 v[48:63], v[34:37], v[164:167], v[48:63]
	ds_read_b128 v[34:37], v72 offset:32768
	s_waitcnt lgkmcnt(0)
	v_mfma_f32_32x32x16_bf16 v[48:63], v[34:37], v[160:163], v[48:63]
	ds_read_b128 v[34:37], v71 offset:32768
	s_waitcnt lgkmcnt(0)
	v_mfma_f32_32x32x16_bf16 v[48:63], v[34:37], v[156:159], v[48:63]
	ds_read_b128 v[34:37], v70 offset:32768
	s_waitcnt lgkmcnt(0)
	v_mfma_f32_32x32x16_bf16 v[48:63], v[34:37], v[152:155], v[48:63]
	ds_read_b128 v[34:37], v69 offset:32768
	s_waitcnt lgkmcnt(0)
	v_mfma_f32_32x32x16_bf16 v[48:63], v[34:37], v[148:151], v[48:63]
	ds_read_b128 v[34:37], v68 offset:32768
	s_waitcnt lgkmcnt(0)
	v_mfma_f32_32x32x16_bf16 v[48:63], v[34:37], v[144:147], v[48:63]
	ds_read_b128 v[34:37], v67 offset:32768
	s_waitcnt lgkmcnt(0)
	v_mfma_f32_32x32x16_bf16 v[48:63], v[34:37], v[140:143], v[48:63]
	ds_read_b128 v[34:37], v66 offset:32768
	s_waitcnt lgkmcnt(0)
	v_mfma_f32_32x32x16_bf16 v[48:63], v[34:37], v[136:139], v[48:63]
	ds_read_b128 v[34:37], v65 offset:32768
	s_waitcnt lgkmcnt(0)
	v_mfma_f32_32x32x16_bf16 v[48:63], v[34:37], v[132:135], v[48:63]
	ds_read_b128 v[34:37], v64 offset:32768
	s_waitcnt lgkmcnt(0)
	v_mfma_f32_32x32x16_bf16 v[48:63], v[34:37], v[128:131], v[48:63]
	ds_read_b128 v[32:35], v32 offset:49152
	s_waitcnt lgkmcnt(0)
	v_mfma_f32_32x32x16_bf16 v[32:47], v[32:35], v[112:115], 0
	v_mfma_f32_32x32x16_bf16 v[32:47], v[78:81], v[184:187], v[32:47]
	ds_read_b128 v[78:81], v77 offset:49152
	s_waitcnt lgkmcnt(0)
	v_mfma_f32_32x32x16_bf16 v[32:47], v[78:81], v[180:183], v[32:47]
	ds_read_b128 v[76:79], v76 offset:49152
	v_add_u32_e32 v80, v245, v207
	ds_read_b128 v[80:83], v80
	s_waitcnt lgkmcnt(1)
	v_mfma_f32_32x32x16_bf16 v[32:47], v[76:79], v[176:179], v[32:47]
	ds_read_b128 v[76:79], v75 offset:49152
	s_waitcnt lgkmcnt(0)
	v_mfma_f32_32x32x16_bf16 v[32:47], v[76:79], v[172:175], v[32:47]
	ds_read_b128 v[74:77], v74 offset:49152
	s_waitcnt lgkmcnt(0)
; #define LAS __attribute__((address_space(3)))
; __device__ __forceinline__ void xattn_unit(LAS unsigned char* lds, const bf16_t* Qx, const bf16_t* KV, int li, int b, int h, int qb, bf16_t* XO, const int tid) {
;     ...
;     for (int kt = 0; kt < 8; ++kt) { f32x16 acc = {}; const lds_cptr kp = (lds_cptr)lds + (32 * kt + r32) * 512;
; #pragma unroll
;         for (int s = 0; s < 16; ++s) { const bf16x8 kf = *(const LAS bf16x8*)(kp + (((2 * s + hi) ^ (r32 & 15)) << 4)); acc = __builtin_amdgcn_mfma_f32_32x32x16_bf16(kf, qf[s], acc, 0, 0, 0); }
;         S[kt] = acc; }
	v_mfma_f32_32x32x16_bf16 v[32:47], v[74:77], v[168:171], v[32:47]
	ds_read_b128 v[74:77], v73 offset:49152
	s_waitcnt lgkmcnt(0)
	v_mfma_f32_32x32x16_bf16 v[32:47], v[74:77], v[164:167], v[32:47]
	ds_read_b128 v[72:75], v72 offset:49152
	s_waitcnt lgkmcnt(0)
	v_mfma_f32_32x32x16_bf16 v[32:47], v[72:75], v[160:163], v[32:47]
	ds_read_b128 v[72:75], v71 offset:49152
	s_waitcnt lgkmcnt(0)
	v_mfma_f32_32x32x16_bf16 v[32:47], v[72:75], v[156:159], v[32:47]
	ds_read_b128 v[70:73], v70 offset:49152
	s_waitcnt lgkmcnt(0)
	v_mfma_f32_32x32x16_bf16 v[32:47], v[70:73], v[152:155], v[32:47]
	ds_read_b128 v[70:73], v69 offset:49152
	s_waitcnt lgkmcnt(0)
	v_mfma_f32_32x32x16_bf16 v[32:47], v[70:73], v[148:151], v[32:47]
	ds_read_b128 v[68:71], v68 offset:49152
	s_waitcnt lgkmcnt(0)
	v_mfma_f32_32x32x16_bf16 v[32:47], v[68:71], v[144:147], v[32:47]
	ds_read_b128 v[68:71], v67 offset:49152
	s_waitcnt lgkmcnt(0)
	v_mfma_f32_32x32x16_bf16 v[32:47], v[68:71], v[140:143], v[32:47]
	ds_read_b128 v[66:69], v66 offset:49152
	s_waitcnt lgkmcnt(0)
	v_mfma_f32_32x32x16_bf16 v[32:47], v[66:69], v[136:139], v[32:47]
	ds_read_b128 v[66:69], v65 offset:49152
	s_waitcnt lgkmcnt(0)
	v_mfma_f32_32x32x16_bf16 v[32:47], v[66:69], v[132:135], v[32:47]
	ds_read_b128 v[64:67], v64 offset:49152
	s_waitcnt lgkmcnt(0)
	v_mfma_f32_32x32x16_bf16 v[32:47], v[64:67], v[128:131], v[32:47]
	v_add_u32_e32 v64, v245, v206
	ds_read_b128 v[64:67], v64
	s_waitcnt lgkmcnt(0)
	v_mfma_f32_32x32x16_bf16 v[64:79], v[64:67], v[112:115], 0
	v_mfma_f32_32x32x16_bf16 v[64:79], v[80:83], v[184:187], v[64:79]
	v_add_u32_e32 v80, v245, v211
	ds_read_b128 v[80:83], v80
	s_waitcnt lgkmcnt(0)
	v_mfma_f32_32x32x16_bf16 v[64:79], v[80:83], v[180:183], v[64:79]
	v_add_u32_e32 v80, v245, v212
	ds_read_b128 v[80:83], v80
	s_waitcnt lgkmcnt(0)
	v_mfma_f32_32x32x16_bf16 v[64:79], v[80:83], v[176:179], v[64:79]
	v_add_u32_e32 v80, v245, v218
	ds_read_b128 v[80:83], v80
	s_waitcnt lgkmcnt(0)
	v_mfma_f32_32x32x16_bf16 v[64:79], v[80:83], v[172:175], v[64:79]
	v_add_u32_e32 v80, v245, v219
	ds_read_b128 v[80:83], v80
	s_waitcnt lgkmcnt(0)
	v_mfma_f32_32x32x16_bf16 v[64:79], v[80:83], v[168:171], v[64:79]
	v_add_u32_e32 v80, v245, v220
	ds_read_b128 v[80:83], v80
	s_waitcnt lgkmcnt(0)
	v_mfma_f32_32x32x16_bf16 v[64:79], v[80:83], v[164:167], v[64:79]
	v_add_u32_e32 v80, v245, v221
	ds_read_b128 v[80:83], v80
	s_waitcnt lgkmcnt(0)
	v_mfma_f32_32x32x16_bf16 v[64:79], v[80:83], v[160:163], v[64:79]
	v_add_u32_e32 v80, v245, v237
	ds_read_b128 v[80:83], v80
	s_waitcnt lgkmcnt(0)
	v_mfma_f32_32x32x16_bf16 v[64:79], v[80:83], v[156:159], v[64:79]
	v_add_u32_e32 v80, v245, v238
	ds_read_b128 v[80:83], v80
	s_waitcnt lgkmcnt(0)
	v_mfma_f32_32x32x16_bf16 v[64:79], v[80:83], v[152:155], v[64:79]
	v_add_u32_e32 v80, v245, v239
	ds_read_b128 v[80:83], v80
	s_waitcnt lgkmcnt(0)
	v_mfma_f32_32x32x16_bf16 v[64:79], v[80:83], v[148:151], v[64:79]
	v_add_u32_e32 v80, v245, v240
	ds_read_b128 v[80:83], v80
	s_waitcnt lgkmcnt(0)
	v_mfma_f32_32x32x16_bf16 v[64:79], v[80:83], v[144:147], v[64:79]
	v_add_u32_e32 v80, v245, v241
	ds_read_b128 v[80:83], v80
	s_waitcnt lgkmcnt(0)
	v_mfma_f32_32x32x16_bf16 v[64:79], v[80:83], v[140:143], v[64:79]
	v_add_u32_e32 v80, v245, v242
	ds_read_b128 v[80:83], v80
	s_waitcnt lgkmcnt(0)
	v_mfma_f32_32x32x16_bf16 v[64:79], v[80:83], v[136:139], v[64:79]
	v_add_u32_e32 v80, v245, v243
	ds_read_b128 v[80:83], v80
	s_waitcnt lgkmcnt(0)
	v_mfma_f32_32x32x16_bf16 v[64:79], v[80:83], v[132:135], v[64:79]
	v_add_u32_e32 v80, v245, v244
	ds_read_b128 v[80:83], v80
	s_waitcnt lgkmcnt(0)
	v_mfma_f32_32x32x16_bf16 v[64:79], v[80:83], v[128:131], v[64:79]
	v_add_u32_e32 v80, v246, v206
	ds_read_b128 v[80:83], v80
	s_waitcnt lgkmcnt(0)
	v_mfma_f32_32x32x16_bf16 v[80:95], v[80:83], v[112:115], 0
	v_mfma_f32_32x32x16_bf16 v[80:95], v[96:99], v[184:187], v[80:95]
	v_add_u32_e32 v96, v246, v211
	ds_read_b128 v[96:99], v96
	s_waitcnt lgkmcnt(0)
	v_mfma_f32_32x32x16_bf16 v[80:95], v[96:99], v[180:183], v[80:95]
	v_add_u32_e32 v96, v246, v212
	ds_read_b128 v[96:99], v96
	s_waitcnt lgkmcnt(0)
	v_mfma_f32_32x32x16_bf16 v[80:95], v[96:99], v[176:179], v[80:95]
	v_add_u32_e32 v96, v246, v218
	ds_read_b128 v[96:99], v96
	s_waitcnt lgkmcnt(0)
	v_mfma_f32_32x32x16_bf16 v[80:95], v[96:99], v[172:175], v[80:95]
	v_add_u32_e32 v96, v246, v219
	ds_read_b128 v[96:99], v96
	s_waitcnt lgkmcnt(0)
	v_mfma_f32_32x32x16_bf16 v[80:95], v[96:99], v[168:171], v[80:95]
	v_add_u32_e32 v96, v246, v220
	ds_read_b128 v[96:99], v96
	s_waitcnt lgkmcnt(0)
	v_mfma_f32_32x32x16_bf16 v[80:95], v[96:99], v[164:167], v[80:95]
	v_add_u32_e32 v96, v246, v221
	ds_read_b128 v[96:99], v96
	s_waitcnt lgkmcnt(0)
	v_mfma_f32_32x32x16_bf16 v[80:95], v[96:99], v[160:163], v[80:95]
	v_add_u32_e32 v96, v246, v237
	ds_read_b128 v[96:99], v96
	s_waitcnt lgkmcnt(0)
	v_mfma_f32_32x32x16_bf16 v[80:95], v[96:99], v[156:159], v[80:95]
	v_add_u32_e32 v96, v246, v238
	ds_read_b128 v[96:99], v96
	s_waitcnt lgkmcnt(0)
	v_mfma_f32_32x32x16_bf16 v[80:95], v[96:99], v[152:155], v[80:95]
	v_add_u32_e32 v96, v246, v239
	ds_read_b128 v[96:99], v96
	s_waitcnt lgkmcnt(0)
	v_mfma_f32_32x32x16_bf16 v[80:95], v[96:99], v[148:151], v[80:95]
	v_add_u32_e32 v96, v246, v240
	ds_read_b128 v[96:99], v96
	s_waitcnt lgkmcnt(0)
	v_mfma_f32_32x32x16_bf16 v[80:95], v[96:99], v[144:147], v[80:95]
	v_add_u32_e32 v96, v246, v241
	ds_read_b128 v[96:99], v96
	s_waitcnt lgkmcnt(0)
	v_mfma_f32_32x32x16_bf16 v[80:95], v[96:99], v[140:143], v[80:95]
	v_add_u32_e32 v96, v246, v242
	ds_read_b128 v[96:99], v96
	s_waitcnt lgkmcnt(0)
	v_mfma_f32_32x32x16_bf16 v[80:95], v[96:99], v[136:139], v[80:95]
	v_add_u32_e32 v96, v246, v243
	ds_read_b128 v[96:99], v96
	s_waitcnt lgkmcnt(0)
; #define LAS __attribute__((address_space(3)))
; __device__ __forceinline__ void xattn_unit(LAS unsigned char* lds, const bf16_t* Qx, const bf16_t* KV, int li, int b, int h, int qb, bf16_t* XO, const int tid) {
;     ...
;     for (int kt = 0; kt < 8; ++kt) { f32x16 acc = {}; const lds_cptr kp = (lds_cptr)lds + (32 * kt + r32) * 512;
; #pragma unroll
;         for (int s = 0; s < 16; ++s) { const bf16x8 kf = *(const LAS bf16x8*)(kp + (((2 * s + hi) ^ (r32 & 15)) << 4)); acc = __builtin_amdgcn_mfma_f32_32x32x16_bf16(kf, qf[s], acc, 0, 0, 0); }
;         S[kt] = acc; }
	v_mfma_f32_32x32x16_bf16 v[80:95], v[96:99], v[132:135], v[80:95]
	v_add_u32_e32 v96, v246, v244
	ds_read_b128 v[96:99], v96
	s_waitcnt lgkmcnt(0)
	v_mfma_f32_32x32x16_bf16 v[80:95], v[96:99], v[128:131], v[80:95]
	v_add_u32_e32 v96, v247, v206
	ds_read_b128 v[96:99], v96
	s_waitcnt lgkmcnt(0)
	v_mfma_f32_32x32x16_bf16 v[96:111], v[96:99], v[112:115], 0
	v_mfma_f32_32x32x16_bf16 v[96:111], v[116:119], v[184:187], v[96:111]
	v_add_u32_e32 v116, v247, v211
	ds_read_b128 v[116:119], v116
	s_waitcnt lgkmcnt(0)
	v_mfma_f32_32x32x16_bf16 v[96:111], v[116:119], v[180:183], v[96:111]
	v_add_u32_e32 v116, v247, v212
	ds_read_b128 v[116:119], v116
	s_waitcnt lgkmcnt(0)
	v_mfma_f32_32x32x16_bf16 v[96:111], v[116:119], v[176:179], v[96:111]
	v_add_u32_e32 v116, v247, v218
	ds_read_b128 v[116:119], v116
	s_waitcnt lgkmcnt(0)
	v_mfma_f32_32x32x16_bf16 v[96:111], v[116:119], v[172:175], v[96:111]
	v_add_u32_e32 v116, v247, v219
	ds_read_b128 v[116:119], v116
	s_waitcnt lgkmcnt(0)
	v_mfma_f32_32x32x16_bf16 v[96:111], v[116:119], v[168:171], v[96:111]
	v_add_u32_e32 v116, v247, v220
	ds_read_b128 v[116:119], v116
	s_waitcnt lgkmcnt(0)
	v_mfma_f32_32x32x16_bf16 v[96:111], v[116:119], v[164:167], v[96:111]
	v_add_u32_e32 v116, v247, v221
	ds_read_b128 v[116:119], v116
	s_waitcnt lgkmcnt(0)
	v_mfma_f32_32x32x16_bf16 v[96:111], v[116:119], v[160:163], v[96:111]
	v_add_u32_e32 v116, v247, v237
	ds_read_b128 v[116:119], v116
	s_waitcnt lgkmcnt(0)
	v_mfma_f32_32x32x16_bf16 v[96:111], v[116:119], v[156:159], v[96:111]
	v_add_u32_e32 v116, v247, v238
	ds_read_b128 v[116:119], v116
	s_waitcnt lgkmcnt(0)
	v_mfma_f32_32x32x16_bf16 v[96:111], v[116:119], v[152:155], v[96:111]
	v_add_u32_e32 v116, v247, v239
	ds_read_b128 v[116:119], v116
	s_waitcnt lgkmcnt(0)
	v_mfma_f32_32x32x16_bf16 v[96:111], v[116:119], v[148:151], v[96:111]
	v_add_u32_e32 v116, v247, v240
	ds_read_b128 v[116:119], v116
	s_waitcnt lgkmcnt(0)
	v_mfma_f32_32x32x16_bf16 v[96:111], v[116:119], v[144:147], v[96:111]
	v_add_u32_e32 v116, v247, v241
	ds_read_b128 v[116:119], v116
	s_waitcnt lgkmcnt(0)
	v_mfma_f32_32x32x16_bf16 v[96:111], v[116:119], v[140:143], v[96:111]
	v_add_u32_e32 v116, v247, v242
	ds_read_b128 v[116:119], v116
	s_waitcnt lgkmcnt(0)
	v_mfma_f32_32x32x16_bf16 v[96:111], v[116:119], v[136:139], v[96:111]
	v_add_u32_e32 v116, v247, v243
	ds_read_b128 v[116:119], v116
	s_waitcnt lgkmcnt(0)
	v_mfma_f32_32x32x16_bf16 v[96:111], v[116:119], v[132:135], v[96:111]
	v_add_u32_e32 v116, v247, v244
	ds_read_b128 v[116:119], v116
	s_waitcnt lgkmcnt(0)
	v_mfma_f32_32x32x16_bf16 v[96:111], v[116:119], v[128:131], v[96:111]
	v_add_u32_e32 v116, v248, v206
	ds_read_b128 v[116:119], v116
	s_waitcnt lgkmcnt(0)
	v_mfma_f32_32x32x16_bf16 v[112:127], v[116:119], v[112:115], 0
	v_mfma_f32_32x32x16_bf16 v[112:127], v[222:225], v[184:187], v[112:127]
	v_add_u32_e32 v184, v248, v211
	ds_read_b128 v[184:187], v184
	s_waitcnt lgkmcnt(0)
	v_mfma_f32_32x32x16_bf16 v[112:127], v[184:187], v[180:183], v[112:127]
	v_add_u32_e32 v180, v248, v212
	ds_read_b128 v[180:183], v180
	s_waitcnt lgkmcnt(0)
	v_mfma_f32_32x32x16_bf16 v[112:127], v[180:183], v[176:179], v[112:127]
	v_add_u32_e32 v176, v248, v218
	ds_read_b128 v[176:179], v176
	s_waitcnt lgkmcnt(0)
	v_mfma_f32_32x32x16_bf16 v[112:127], v[176:179], v[172:175], v[112:127]
	v_add_u32_e32 v172, v248, v219
	ds_read_b128 v[172:175], v172
	s_waitcnt lgkmcnt(0)
	v_mfma_f32_32x32x16_bf16 v[112:127], v[172:175], v[168:171], v[112:127]
	v_add_u32_e32 v168, v248, v220
	ds_read_b128 v[168:171], v168
	s_waitcnt lgkmcnt(0)
	v_mfma_f32_32x32x16_bf16 v[112:127], v[168:171], v[164:167], v[112:127]
	v_add_u32_e32 v164, v248, v221
	ds_read_b128 v[164:167], v164
	s_waitcnt lgkmcnt(0)
	v_mfma_f32_32x32x16_bf16 v[112:127], v[164:167], v[160:163], v[112:127]
	v_add_u32_e32 v160, v248, v237
	ds_read_b128 v[160:163], v160
	s_waitcnt lgkmcnt(0)
	v_mfma_f32_32x32x16_bf16 v[112:127], v[160:163], v[156:159], v[112:127]
	v_add_u32_e32 v156, v248, v238
	ds_read_b128 v[156:159], v156
	s_waitcnt lgkmcnt(0)
	v_mfma_f32_32x32x16_bf16 v[112:127], v[156:159], v[152:155], v[112:127]
	v_add_u32_e32 v152, v248, v239
	ds_read_b128 v[152:155], v152
	s_waitcnt lgkmcnt(0)
	v_mfma_f32_32x32x16_bf16 v[112:127], v[152:155], v[148:151], v[112:127]
	v_add_u32_e32 v148, v248, v240
	ds_read_b128 v[148:151], v148
	s_waitcnt lgkmcnt(0)
	v_mfma_f32_32x32x16_bf16 v[112:127], v[148:151], v[144:147], v[112:127]
	v_add_u32_e32 v144, v248, v241
	ds_read_b128 v[144:147], v144
	s_waitcnt lgkmcnt(0)
	v_mfma_f32_32x32x16_bf16 v[112:127], v[144:147], v[140:143], v[112:127]
	v_add_u32_e32 v140, v248, v242
	ds_read_b128 v[140:143], v140
	s_waitcnt lgkmcnt(0)
	v_mfma_f32_32x32x16_bf16 v[112:127], v[140:143], v[136:139], v[112:127]
	v_add_u32_e32 v136, v248, v243
	ds_read_b128 v[136:139], v136
	s_waitcnt lgkmcnt(0)
	v_mfma_f32_32x32x16_bf16 v[112:127], v[136:139], v[132:135], v[112:127]
	v_add_u32_e32 v132, v248, v244
	ds_read_b128 v[132:135], v132
	s_waitcnt lgkmcnt(0)
; __device__ __forceinline__ float shx(float v, int lane, int mask) { return __builtin_bit_cast(float, __builtin_amdgcn_ds_bpermute((lane ^ mask) << 2, __builtin_bit_cast(int, v))); }
; __device__ __forceinline__ void xattn_unit(LAS unsigned char* lds, const bf16_t* Qx, const bf16_t* KV, int li, int b, int h, int qb, bf16_t* XO, const int tid) {
;     ...
;     float m = S[0][0];
; #pragma unroll
;     for (int kt = 0; kt < 8; ++kt)
; #pragma unroll
;         for (int r = 0; r < 16; ++r) m = fmaxf(m, S[kt][r]);
;     m = fmaxf(m, pg8::shx(m, lane, 32));
;     float l = 0.f;
; #pragma unroll
;     for (int kt = 0; kt < 8; ++kt)
; #pragma unroll
;         for (int r = 0; r < 16; ++r) { const float p = __builtin_amdgcn_exp2f(S[kt][r] - m); S[kt][r] = p; l += p; }
	v_mfma_f32_32x32x16_bf16 v[112:127], v[132:135], v[128:131], v[112:127]
	v_max_f32_e32 v128, v1, v1
	v_max_f32_e32 v129, v0, v0
	v_max_f32_e32 v128, v129, v128
	v_max3_f32 v128, v128, v2, v3
	v_max3_f32 v128, v128, v4, v5
	v_max3_f32 v128, v128, v6, v7
	v_max3_f32 v128, v128, v8, v9
	v_max3_f32 v128, v128, v10, v11
	v_max3_f32 v128, v128, v12, v13
	v_max3_f32 v128, v128, v14, v15
	v_max3_f32 v128, v128, v16, v17
	v_max3_f32 v128, v128, v18, v19
	v_max3_f32 v128, v128, v20, v21
	v_max3_f32 v128, v128, v22, v23
	v_max3_f32 v128, v128, v24, v25
	v_max3_f32 v128, v128, v26, v27
	v_max3_f32 v128, v128, v28, v29
	v_max3_f32 v128, v128, v30, v31
	v_max3_f32 v128, v128, v48, v49
	v_max3_f32 v128, v128, v50, v51
	v_max3_f32 v128, v128, v52, v53
	v_max3_f32 v128, v128, v54, v55
	v_max3_f32 v128, v128, v56, v57
	v_max3_f32 v128, v128, v58, v59
	v_max3_f32 v128, v128, v60, v61
	v_max3_f32 v128, v128, v62, v63
	v_max3_f32 v128, v128, v32, v33
	v_max3_f32 v128, v128, v34, v35
	v_max3_f32 v128, v128, v36, v37
	v_max3_f32 v128, v128, v38, v39
	v_max3_f32 v128, v128, v40, v41
	v_max3_f32 v128, v128, v42, v43
	v_max3_f32 v128, v128, v44, v45
	v_max3_f32 v128, v128, v46, v47
	v_max3_f32 v128, v128, v64, v65
	v_max3_f32 v128, v128, v66, v67
	v_max3_f32 v128, v128, v68, v69
	v_max3_f32 v128, v128, v70, v71
	v_max3_f32 v128, v128, v72, v73
	v_max3_f32 v128, v128, v74, v75
	v_max3_f32 v128, v128, v76, v77
	v_max3_f32 v128, v128, v78, v79
	v_max3_f32 v128, v128, v80, v81
	v_max3_f32 v128, v128, v82, v83
	v_max3_f32 v128, v128, v84, v85
	v_max3_f32 v128, v128, v86, v87
	v_max3_f32 v128, v128, v88, v89
	v_max3_f32 v128, v128, v90, v91
	v_max3_f32 v128, v128, v92, v93
	v_max3_f32 v128, v128, v94, v95
	v_max3_f32 v128, v128, v96, v97
	v_max3_f32 v128, v128, v98, v99
	v_max3_f32 v128, v128, v100, v101
	v_max3_f32 v128, v128, v102, v103
	v_max3_f32 v128, v128, v104, v105
	v_max3_f32 v128, v128, v106, v107
	v_max3_f32 v128, v128, v108, v109
	v_max3_f32 v128, v128, v110, v111
	v_max3_f32 v128, v128, v112, v113
	v_max3_f32 v128, v128, v114, v115
	v_max3_f32 v128, v128, v116, v117
	v_max3_f32 v128, v128, v118, v119
	v_max3_f32 v128, v128, v120, v121
	v_max3_f32 v128, v128, v122, v123
	v_max3_f32 v128, v128, v124, v125
	v_max3_f32 v128, v128, v126, v127
	ds_bpermute_b32 v129, v249, v128
	s_waitcnt lgkmcnt(0)
	v_max_f32_e32 v129, v129, v129
	v_max_f32_e32 v128, v128, v129
	v_sub_f32_e32 v0, v0, v128
	v_exp_f32_e32 v0, v0
	v_sub_f32_e32 v1, v1, v128
	v_exp_f32_e32 v1, v1
	v_sub_f32_e32 v2, v2, v128
	v_exp_f32_e32 v2, v2
	v_sub_f32_e32 v3, v3, v128
	v_exp_f32_e32 v3, v3
	v_sub_f32_e32 v4, v4, v128
	v_add_f32_e32 v129, 0, v0
	v_exp_f32_e32 v4, v4
	v_sub_f32_e32 v5, v5, v128
	v_add_f32_e32 v129, v1, v129
	v_exp_f32_e32 v5, v5
	v_sub_f32_e32 v6, v6, v128
	v_add_f32_e32 v129, v2, v129
	v_exp_f32_e32 v6, v6
	v_sub_f32_e32 v7, v7, v128
	v_add_f32_e32 v129, v3, v129
	v_exp_f32_e32 v7, v7
	v_sub_f32_e32 v8, v8, v128
	v_add_f32_e32 v129, v4, v129
	v_exp_f32_e32 v8, v8
	v_sub_f32_e32 v9, v9, v128
	v_add_f32_e32 v129, v5, v129
	v_exp_f32_e32 v9, v9
	v_sub_f32_e32 v10, v10, v128
	v_add_f32_e32 v129, v6, v129
	v_exp_f32_e32 v10, v10
	v_sub_f32_e32 v11, v11, v128
	v_add_f32_e32 v129, v7, v129
	v_exp_f32_e32 v11, v11
	v_sub_f32_e32 v12, v12, v128
	v_add_f32_e32 v129, v8, v129
	v_exp_f32_e32 v12, v12
	v_sub_f32_e32 v13, v13, v128
	v_add_f32_e32 v129, v9, v129
	v_exp_f32_e32 v13, v13
	v_sub_f32_e32 v14, v14, v128
	v_add_f32_e32 v129, v10, v129
	v_exp_f32_e32 v14, v14
	v_sub_f32_e32 v15, v15, v128
	v_add_f32_e32 v129, v11, v129
	v_exp_f32_e32 v15, v15
	v_add_f32_e32 v129, v12, v129
	v_add_f32_e32 v129, v13, v129
	v_add_f32_e32 v129, v14, v129
	v_sub_f32_e32 v16, v16, v128
	v_add_f32_e32 v130, v15, v129
	v_exp_f32_e32 v129, v16
	v_sub_f32_e32 v17, v17, v128
	v_add_f32_e32 v16, v129, v130
	v_exp_f32_e32 v130, v17
	v_sub_f32_e32 v17, v18, v128
	v_exp_f32_e32 v131, v17
	v_sub_f32_e32 v17, v19, v128
	v_exp_f32_e32 v132, v17
	v_sub_f32_e32 v17, v20, v128
	v_exp_f32_e32 v133, v17
	v_sub_f32_e32 v17, v21, v128
	v_add_f32_e32 v16, v130, v16
	v_exp_f32_e32 v134, v17
	v_sub_f32_e32 v17, v22, v128
	v_add_f32_e32 v16, v131, v16
	v_exp_f32_e32 v135, v17
	v_sub_f32_e32 v17, v23, v128
	v_add_f32_e32 v16, v132, v16
	v_exp_f32_e32 v136, v17
	v_sub_f32_e32 v17, v24, v128
	v_add_f32_e32 v16, v133, v16
	v_exp_f32_e32 v137, v17
	v_sub_f32_e32 v17, v25, v128
	v_add_f32_e32 v16, v134, v16
	v_exp_f32_e32 v138, v17
	v_sub_f32_e32 v17, v26, v128
	v_add_f32_e32 v16, v135, v16
	v_exp_f32_e32 v139, v17
	v_sub_f32_e32 v17, v27, v128
	v_add_f32_e32 v16, v136, v16
	v_exp_f32_e32 v140, v17
	v_sub_f32_e32 v17, v28, v128
	v_add_f32_e32 v16, v137, v16
	v_exp_f32_e32 v141, v17
	v_sub_f32_e32 v17, v29, v128
	v_add_f32_e32 v16, v138, v16
	v_exp_f32_e32 v142, v17
	v_sub_f32_e32 v17, v30, v128
	v_add_f32_e32 v16, v139, v16
	v_exp_f32_e32 v143, v17
	v_sub_f32_e32 v17, v31, v128
	v_add_f32_e32 v16, v140, v16
	v_exp_f32_e32 v31, v17
	v_sub_f32_e32 v17, v48, v128
	v_add_f32_e32 v16, v141, v16
	v_exp_f32_e32 v48, v17
	v_sub_f32_e32 v17, v49, v128
	v_add_f32_e32 v16, v142, v16
	v_exp_f32_e32 v49, v17
	v_sub_f32_e32 v17, v50, v128
	v_add_f32_e32 v16, v143, v16
	v_exp_f32_e32 v50, v17
	v_sub_f32_e32 v17, v51, v128
	v_add_f32_e32 v16, v31, v16
	v_exp_f32_e32 v51, v17
	v_sub_f32_e32 v17, v52, v128
	v_add_f32_e32 v16, v48, v16
	v_exp_f32_e32 v52, v17
	v_sub_f32_e32 v17, v53, v128
	v_add_f32_e32 v16, v49, v16
	v_exp_f32_e32 v53, v17
	v_sub_f32_e32 v17, v54, v128
	v_add_f32_e32 v16, v50, v16
	v_exp_f32_e32 v54, v17
	v_sub_f32_e32 v17, v55, v128
	v_add_f32_e32 v16, v51, v16
	v_exp_f32_e32 v55, v17
	v_sub_f32_e32 v17, v56, v128
	v_add_f32_e32 v16, v52, v16
; __device__ __forceinline__ void xattn_unit(LAS unsigned char* lds, const bf16_t* Qx, const bf16_t* KV, int li, int b, int h, int qb, bf16_t* XO, const int tid) {
;     ...
;         for (int r = 0; r < 16; ++r) { const float p = __builtin_amdgcn_exp2f(S[kt][r] - m); S[kt][r] = p; l += p; }
	v_exp_f32_e32 v56, v17
	v_sub_f32_e32 v17, v57, v128
	v_add_f32_e32 v16, v53, v16
	v_exp_f32_e32 v57, v17
	v_sub_f32_e32 v17, v58, v128
	v_add_f32_e32 v16, v54, v16
	v_exp_f32_e32 v58, v17
	v_sub_f32_e32 v17, v59, v128
	v_add_f32_e32 v16, v55, v16
	v_exp_f32_e32 v59, v17
	v_sub_f32_e32 v17, v60, v128
	v_add_f32_e32 v16, v56, v16
	v_exp_f32_e32 v60, v17
	v_sub_f32_e32 v17, v61, v128
	v_add_f32_e32 v16, v57, v16
	v_exp_f32_e32 v61, v17
	v_sub_f32_e32 v17, v62, v128
	v_add_f32_e32 v16, v58, v16
	v_exp_f32_e32 v62, v17
	v_sub_f32_e32 v17, v63, v128
	v_add_f32_e32 v16, v59, v16
	v_exp_f32_e32 v63, v17
	v_sub_f32_e32 v17, v32, v128
	v_add_f32_e32 v16, v60, v16
	v_exp_f32_e32 v144, v17
	v_sub_f32_e32 v17, v33, v128
	v_add_f32_e32 v16, v61, v16
	v_exp_f32_e32 v145, v17
	v_sub_f32_e32 v17, v34, v128
	v_add_f32_e32 v16, v62, v16
	v_exp_f32_e32 v146, v17
	v_sub_f32_e32 v17, v35, v128
	v_add_f32_e32 v16, v63, v16
	v_exp_f32_e32 v147, v17
	v_sub_f32_e32 v17, v36, v128
	v_add_f32_e32 v16, v144, v16
	v_exp_f32_e32 v148, v17
	v_sub_f32_e32 v17, v37, v128
	v_add_f32_e32 v16, v145, v16
	v_exp_f32_e32 v149, v17
	v_sub_f32_e32 v17, v38, v128
	v_add_f32_e32 v16, v146, v16
	v_exp_f32_e32 v150, v17
	v_sub_f32_e32 v17, v39, v128
	v_add_f32_e32 v16, v147, v16
	v_exp_f32_e32 v151, v17
	v_sub_f32_e32 v17, v40, v128
	v_add_f32_e32 v16, v148, v16
	v_exp_f32_e32 v152, v17
	v_sub_f32_e32 v17, v41, v128
	v_add_f32_e32 v16, v149, v16
	v_exp_f32_e32 v153, v17
	v_sub_f32_e32 v17, v42, v128
	v_add_f32_e32 v16, v150, v16
	v_exp_f32_e32 v154, v17
	v_sub_f32_e32 v17, v43, v128
	v_add_f32_e32 v16, v151, v16
	v_exp_f32_e32 v155, v17
	v_sub_f32_e32 v17, v44, v128
	v_add_f32_e32 v16, v152, v16
	v_exp_f32_e32 v156, v17
	v_sub_f32_e32 v17, v45, v128
	v_add_f32_e32 v16, v153, v16
	v_exp_f32_e32 v157, v17
	v_sub_f32_e32 v17, v46, v128
	v_add_f32_e32 v16, v154, v16
	v_exp_f32_e32 v158, v17
	v_sub_f32_e32 v17, v47, v128
	v_add_f32_e32 v16, v155, v16
	v_exp_f32_e32 v47, v17
	v_sub_f32_e32 v17, v64, v128
	v_add_f32_e32 v16, v156, v16
	v_exp_f32_e32 v64, v17
	v_sub_f32_e32 v17, v65, v128
	v_add_f32_e32 v16, v157, v16
	v_exp_f32_e32 v65, v17
	v_sub_f32_e32 v17, v66, v128
	v_add_f32_e32 v16, v158, v16
	v_exp_f32_e32 v66, v17
	v_sub_f32_e32 v17, v67, v128
	v_add_f32_e32 v16, v47, v16
	v_exp_f32_e32 v67, v17
	v_sub_f32_e32 v17, v68, v128
	v_add_f32_e32 v16, v64, v16
	v_exp_f32_e32 v68, v17
	v_sub_f32_e32 v17, v69, v128
	v_add_f32_e32 v16, v65, v16
	v_exp_f32_e32 v69, v17
	v_sub_f32_e32 v17, v70, v128
	v_add_f32_e32 v16, v66, v16
	v_exp_f32_e32 v70, v17
	v_sub_f32_e32 v17, v71, v128
	v_add_f32_e32 v16, v67, v16
	v_exp_f32_e32 v71, v17
	v_sub_f32_e32 v17, v72, v128
	v_add_f32_e32 v16, v68, v16
	v_exp_f32_e32 v72, v17
	v_sub_f32_e32 v17, v73, v128
	v_add_f32_e32 v16, v69, v16
	v_exp_f32_e32 v73, v17
	v_sub_f32_e32 v17, v74, v128
	v_add_f32_e32 v16, v70, v16
	v_exp_f32_e32 v74, v17
	v_sub_f32_e32 v17, v75, v128
	v_add_f32_e32 v16, v71, v16
	v_exp_f32_e32 v75, v17
	v_sub_f32_e32 v17, v76, v128
	v_add_f32_e32 v16, v72, v16
	v_exp_f32_e32 v76, v17
	v_sub_f32_e32 v17, v77, v128
	v_add_f32_e32 v16, v73, v16
	v_exp_f32_e32 v77, v17
	v_sub_f32_e32 v17, v78, v128
	v_add_f32_e32 v16, v74, v16
	v_exp_f32_e32 v78, v17
	v_sub_f32_e32 v17, v79, v128
	v_add_f32_e32 v16, v75, v16
	v_exp_f32_e32 v79, v17
	v_sub_f32_e32 v17, v80, v128
	v_add_f32_e32 v16, v76, v16
	v_exp_f32_e32 v159, v17
	v_sub_f32_e32 v17, v81, v128
	v_add_f32_e32 v16, v77, v16
	v_exp_f32_e32 v160, v17
	v_sub_f32_e32 v17, v82, v128
	v_add_f32_e32 v16, v78, v16
	v_exp_f32_e32 v82, v17
	v_sub_f32_e32 v17, v83, v128
	v_add_f32_e32 v16, v79, v16
	v_exp_f32_e32 v83, v17
	v_sub_f32_e32 v17, v84, v128
	v_add_f32_e32 v16, v159, v16
	v_exp_f32_e32 v84, v17
	v_sub_f32_e32 v17, v85, v128
	v_add_f32_e32 v16, v160, v16
	v_exp_f32_e32 v85, v17
	v_sub_f32_e32 v17, v86, v128
	v_add_f32_e32 v16, v82, v16
	v_exp_f32_e32 v86, v17
	v_sub_f32_e32 v17, v87, v128
	v_add_f32_e32 v16, v83, v16
	v_exp_f32_e32 v87, v17
	v_sub_f32_e32 v17, v88, v128
	v_add_f32_e32 v16, v84, v16
	v_exp_f32_e32 v88, v17
	v_sub_f32_e32 v17, v89, v128
	v_add_f32_e32 v16, v85, v16
	v_exp_f32_e32 v89, v17
	v_sub_f32_e32 v17, v90, v128
	v_add_f32_e32 v16, v86, v16
	v_exp_f32_e32 v90, v17
	v_sub_f32_e32 v17, v91, v128
	v_add_f32_e32 v16, v87, v16
	v_exp_f32_e32 v91, v17
	v_sub_f32_e32 v17, v92, v128
	v_add_f32_e32 v16, v88, v16
	v_exp_f32_e32 v92, v17
	v_sub_f32_e32 v17, v93, v128
	v_add_f32_e32 v16, v89, v16
	v_exp_f32_e32 v93, v17
	v_sub_f32_e32 v17, v94, v128
	v_add_f32_e32 v16, v90, v16
	v_exp_f32_e32 v94, v17
	v_sub_f32_e32 v17, v95, v128
	v_add_f32_e32 v16, v91, v16
	v_exp_f32_e32 v95, v17
	v_sub_f32_e32 v17, v96, v128
	v_add_f32_e32 v16, v92, v16
	v_exp_f32_e32 v96, v17
	v_sub_f32_e32 v17, v97, v128
	v_add_f32_e32 v16, v93, v16
	v_exp_f32_e32 v97, v17
	v_sub_f32_e32 v17, v98, v128
	v_add_f32_e32 v16, v94, v16
	v_exp_f32_e32 v98, v17
	v_sub_f32_e32 v17, v99, v128
	v_add_f32_e32 v16, v95, v16
	v_exp_f32_e32 v99, v17
	v_sub_f32_e32 v17, v100, v128
	v_add_f32_e32 v16, v96, v16
	v_exp_f32_e32 v100, v17
	v_sub_f32_e32 v17, v101, v128
	v_add_f32_e32 v16, v97, v16
	v_exp_f32_e32 v101, v17
	v_sub_f32_e32 v17, v102, v128
	v_add_f32_e32 v16, v98, v16
	v_exp_f32_e32 v102, v17
	v_sub_f32_e32 v17, v103, v128
	v_add_f32_e32 v16, v99, v16
	v_exp_f32_e32 v103, v17
	v_sub_f32_e32 v17, v104, v128
	v_add_f32_e32 v16, v100, v16
	v_exp_f32_e32 v104, v17
	v_sub_f32_e32 v17, v105, v128
	v_add_f32_e32 v16, v101, v16
; __device__ __forceinline__ float shx(float v, int lane, int mask) { return __builtin_bit_cast(float, __builtin_amdgcn_ds_bpermute((lane ^ mask) << 2, __builtin_bit_cast(int, v))); }
; __device__ __forceinline__ void glds16(const void* gsrc, LAS unsigned char* dst_uniform) { __builtin_amdgcn_global_load_lds((const unsigned*)gsrc, (LAS unsigned*)dst_uniform, 16, 0, 0); }
; #define ATT_SYNC() do { asm volatile("s_waitcnt vmcnt(0) lgkmcnt(0)" ::: "memory"); __syncthreads(); } while (0)
; __device__ __forceinline__ void xattn_unit(LAS unsigned char* lds, const bf16_t* Qx, const bf16_t* KV, int li, int b, int h, int qb, bf16_t* XO, const int tid) {
;     ...
;         for (int r = 0; r < 16; ++r) { const float p = __builtin_amdgcn_exp2f(S[kt][r] - m); S[kt][r] = p; l += p; }
;     l += pg8::shx(l, lane, 32);
;     const float inv = __builtin_amdgcn_rcpf(l);
;     bf16x8 pf[16];
; #pragma unroll
;     for (int kt = 0; kt < 8; ++kt) { pf[2 * kt] = pack8(S[kt], 0); pf[2 * kt + 1] = pack8(S[kt], 8); }
;     ATT_SYNC();
;     const bf16_t* Vb = Kb + 1024;
; #pragma unroll 4
;     for (int ii = 0; ii < 16; ++ii) { const int i = wid * 16 + ii, d0 = i >> 4, ks = i & 15, key = 16 * ks + 8 * hi + ((lane >> 2) & 7), cc = lane & 3;
;         glds16(Vb + (size_t)key * 8192 + 32 * d0 + 8 * cc, lds + i * 1024); }
;     ATT_SYNC();
;     const lds_cptr vb = (lds_cptr)lds + ((lane >> 4) & 1) * 32 + (lane & 3) * 8 + (4 * hi + ((lane & 15) >> 2)) * 64;
;     bf16_t* orow = XO + tok * 1024 + h * 256;
	v_exp_f32_e32 v105, v17
	v_sub_f32_e32 v17, v106, v128
	v_add_f32_e32 v16, v102, v16
	v_exp_f32_e32 v106, v17
	v_sub_f32_e32 v17, v107, v128
	v_add_f32_e32 v16, v103, v16
	v_exp_f32_e32 v107, v17
	v_sub_f32_e32 v17, v108, v128
	v_add_f32_e32 v16, v104, v16
	v_exp_f32_e32 v108, v17
	v_sub_f32_e32 v17, v109, v128
	v_add_f32_e32 v16, v105, v16
	v_exp_f32_e32 v109, v17
	v_sub_f32_e32 v17, v110, v128
	v_add_f32_e32 v16, v106, v16
	v_exp_f32_e32 v110, v17
	v_sub_f32_e32 v17, v111, v128
	v_add_f32_e32 v16, v107, v16
	v_exp_f32_e32 v111, v17
	v_sub_f32_e32 v17, v112, v128
	v_add_f32_e32 v16, v108, v16
	v_exp_f32_e32 v112, v17
	v_sub_f32_e32 v17, v113, v128
	v_add_f32_e32 v16, v109, v16
	v_exp_f32_e32 v113, v17
	v_sub_f32_e32 v17, v114, v128
	v_add_f32_e32 v16, v110, v16
	v_exp_f32_e32 v114, v17
	v_sub_f32_e32 v17, v115, v128
	v_add_f32_e32 v16, v111, v16
	v_exp_f32_e32 v115, v17
	v_sub_f32_e32 v17, v116, v128
	v_add_f32_e32 v16, v112, v16
	v_exp_f32_e32 v116, v17
	v_sub_f32_e32 v17, v117, v128
	v_add_f32_e32 v16, v113, v16
	v_exp_f32_e32 v117, v17
	v_sub_f32_e32 v17, v118, v128
	v_add_f32_e32 v16, v114, v16
	v_exp_f32_e32 v118, v17
	v_sub_f32_e32 v17, v119, v128
	v_add_f32_e32 v16, v115, v16
	v_exp_f32_e32 v119, v17
	v_sub_f32_e32 v17, v120, v128
	v_add_f32_e32 v16, v116, v16
	v_exp_f32_e32 v120, v17
	v_sub_f32_e32 v17, v121, v128
	v_add_f32_e32 v16, v117, v16
	v_exp_f32_e32 v121, v17
	v_sub_f32_e32 v17, v122, v128
	v_add_f32_e32 v16, v118, v16
	v_exp_f32_e32 v122, v17
	v_sub_f32_e32 v17, v123, v128
	v_add_f32_e32 v16, v119, v16
	v_exp_f32_e32 v123, v17
	v_sub_f32_e32 v17, v124, v128
	v_add_f32_e32 v16, v120, v16
	v_exp_f32_e32 v124, v17
	v_sub_f32_e32 v17, v125, v128
	v_add_f32_e32 v16, v121, v16
	v_exp_f32_e32 v125, v17
	v_sub_f32_e32 v17, v126, v128
	v_add_f32_e32 v16, v122, v16
	v_exp_f32_e32 v126, v17
	v_sub_f32_e32 v17, v127, v128
	v_add_f32_e32 v16, v123, v16
	v_exp_f32_e32 v127, v17
	v_add_f32_e32 v16, v124, v16
	v_add_f32_e32 v16, v125, v16
	v_add_f32_e32 v16, v126, v16
	v_add_f32_e32 v80, v127, v16
	ds_bpermute_b32 v81, v249, v80
	v_cvt_pk_bf16_f32 v16, v0, v1
	v_cvt_pk_bf16_f32 v17, v2, v3
	v_cvt_pk_bf16_f32 v18, v4, v5
	v_cvt_pk_bf16_f32 v19, v6, v7
	v_cvt_pk_bf16_f32 v20, v8, v9
	v_cvt_pk_bf16_f32 v21, v10, v11
	v_cvt_pk_bf16_f32 v22, v12, v13
	v_cvt_pk_bf16_f32 v23, v14, v15
	v_cvt_pk_bf16_f32 v24, v129, v130
	v_cvt_pk_bf16_f32 v25, v131, v132
	v_cvt_pk_bf16_f32 v26, v133, v134
	v_cvt_pk_bf16_f32 v27, v135, v136
	v_cvt_pk_bf16_f32 v28, v137, v138
	v_cvt_pk_bf16_f32 v29, v139, v140
	v_cvt_pk_bf16_f32 v30, v141, v142
	v_cvt_pk_bf16_f32 v31, v143, v31
	v_cvt_pk_bf16_f32 v32, v48, v49
	v_cvt_pk_bf16_f32 v33, v50, v51
	v_cvt_pk_bf16_f32 v34, v52, v53
	v_cvt_pk_bf16_f32 v35, v54, v55
	v_cvt_pk_bf16_f32 v36, v56, v57
	v_cvt_pk_bf16_f32 v37, v58, v59
	v_cvt_pk_bf16_f32 v38, v60, v61
	v_cvt_pk_bf16_f32 v39, v62, v63
	v_cvt_pk_bf16_f32 v40, v144, v145
	v_cvt_pk_bf16_f32 v41, v146, v147
	v_cvt_pk_bf16_f32 v42, v148, v149
	v_cvt_pk_bf16_f32 v43, v150, v151
	v_cvt_pk_bf16_f32 v44, v152, v153
	v_cvt_pk_bf16_f32 v45, v154, v155
	v_cvt_pk_bf16_f32 v46, v156, v157
	v_cvt_pk_bf16_f32 v47, v158, v47
	v_cvt_pk_bf16_f32 v48, v64, v65
	v_cvt_pk_bf16_f32 v49, v66, v67
	v_cvt_pk_bf16_f32 v50, v68, v69
	v_cvt_pk_bf16_f32 v51, v70, v71
	v_cvt_pk_bf16_f32 v52, v72, v73
	v_cvt_pk_bf16_f32 v53, v74, v75
	v_cvt_pk_bf16_f32 v54, v76, v77
	v_cvt_pk_bf16_f32 v55, v78, v79
	v_cvt_pk_bf16_f32 v56, v159, v160
	v_cvt_pk_bf16_f32 v57, v82, v83
	v_cvt_pk_bf16_f32 v58, v84, v85
	v_cvt_pk_bf16_f32 v59, v86, v87
	v_cvt_pk_bf16_f32 v60, v88, v89
	v_cvt_pk_bf16_f32 v61, v90, v91
	v_cvt_pk_bf16_f32 v62, v92, v93
	v_cvt_pk_bf16_f32 v63, v94, v95
	v_cvt_pk_bf16_f32 v64, v96, v97
	v_cvt_pk_bf16_f32 v65, v98, v99
	v_cvt_pk_bf16_f32 v66, v100, v101
	v_cvt_pk_bf16_f32 v67, v102, v103
	v_cvt_pk_bf16_f32 v68, v104, v105
	v_cvt_pk_bf16_f32 v69, v106, v107
	v_cvt_pk_bf16_f32 v70, v108, v109
	v_cvt_pk_bf16_f32 v71, v110, v111
	v_cvt_pk_bf16_f32 v72, v112, v113
	v_cvt_pk_bf16_f32 v73, v114, v115
	v_cvt_pk_bf16_f32 v74, v116, v117
	v_cvt_pk_bf16_f32 v75, v118, v119
	v_cvt_pk_bf16_f32 v76, v120, v121
	v_cvt_pk_bf16_f32 v77, v122, v123
	v_cvt_pk_bf16_f32 v78, v124, v125
	v_cvt_pk_bf16_f32 v79, v126, v127
	s_waitcnt vmcnt(0) lgkmcnt(0)
	v_lshl_add_u64 v[0:1], v[188:189], 0, s[0:1]
	v_lshl_add_u64 v[2:3], v[190:191], 0, s[0:1]
	v_lshl_add_u64 v[4:5], v[192:193], 0, s[0:1]
	v_lshl_add_u64 v[6:7], v[194:195], 0, s[0:1]
	s_mov_b64 s[0:1], 0
	s_waitcnt lgkmcnt(0)
	s_barrier
	.p2alignl 6, 3212836864
.LBB0_434:
	v_lshl_add_u64 v[8:9], v[6:7], 0, s[0:1]
	s_mov_b32 m0, s24
	s_nop 0
	global_load_lds_dwordx4 v[8:9], off
	v_lshl_add_u64 v[8:9], v[4:5], 0, s[0:1]
	s_add_i32 m0, s24, 0x400
	s_nop 0
	global_load_lds_dwordx4 v[8:9], off
	v_lshl_add_u64 v[8:9], v[2:3], 0, s[0:1]
	s_add_i32 m0, s24, 0x800
	s_nop 0
	global_load_lds_dwordx4 v[8:9], off
	v_lshl_add_u64 v[8:9], v[0:1], 0, s[0:1]
	s_add_i32 m0, s24, 0xc00
	s_add_u32 s0, s0, 0x100000
	global_load_lds_dwordx4 v[8:9], off
	s_addc_u32 s1, s1, 0
	s_addk_i32 s24, 0x1000
	s_cmp_eq_u32 s0, 0x400000
	s_cbranch_scc0 .LBB0_434
	v_add_f32_e32 v0, v80, v81
	v_rcp_f32_e32 v82, v0
	s_waitcnt vmcnt(0) lgkmcnt(0)
	v_lshl_add_u64 v[0:1], v[200:201], 1, s[10:11]
	v_lshl_add_u64 v[0:1], s[12:13], 1, v[0:1]
	v_mov_b32_e32 v199, v209
	v_lshl_add_u64 v[80:81], v[0:1], 0, v[198:199]
	s_mov_b32 s0, 0
	s_waitcnt vmcnt(0) lgkmcnt(0)
	s_barrier
	.p2alignl 6, 3212836864

; __device__ __forceinline__ void dil_unit(LAS unsigned char* lds, const LAS float* btab, const bf16_t* QKV, int gi, int ldil, int b, int h, int r, int ub, bf16_t* AO, float* lseacc, const int tid) {
;     const int lane = tid & 63, wid = __builtin_amdgcn_readfirstlane(tid >> 6), r32 = lane & 31, hi = lane >> 5;
;     const int sub_len = SEQ >> ldil, k0 = ub * 256 - 64;
;     const size_t tokb = (size_t)b * SEQ + r;
;     const bf16_t* base = QKV + h * 128;
; #pragma unroll 4
;     for (int ii = 0; ii < 12; ++ii) { const int i = wid * 12 + ii, kk = 4 * i + (lane >> 4), c = (lane & 15) ^ (kk & 15); int ki = k0 + kk; ki = ki < 0 ? 0 : (ki >= sub_len ? sub_len - 1 : ki);
.LBB0_662:
	s_or_b64 exec, exec, s[0:1]
	s_and_b32 s1, s19, 15
	s_ashr_i32 s0, s19, 7
	s_and_b32 s2, s1, s16
	s_lshr_b32 s1, s1, s12
	s_lshl_b32 s27, s1, 8
	s_ashr_i32 s1, s0, 31
	v_readfirstlane_b32 s3, v237
	s_lshl_b64 s[0:1], s[0:1], 12
	s_ashr_i32 s20, s3, 6
	s_or_b32 s0, s0, s2
	s_lshl_b32 s24, s21, 7
	s_lshl_b32 s2, s21, 8
	s_add_u32 s2, s14, s2
	s_mul_i32 s25, s20, 0x3000
	s_addc_u32 s3, s15, 0
	s_add_i32 s26, s25, 0
	s_mul_i32 s25, s20, 48
	v_bfe_u32 v0, v237, 4, 2
	s_add_i32 s28, s25, s27
	v_and_b32_e32 v238, 63, v237
	v_or_b32_e32 v2, s28, v0
	v_or_b32_e32 v3, s25, v0
	s_mov_b32 s25, 0
	s_mov_b32 s28, s26
	s_movk_i32 s36, 0x1800
	s_mov_b64 s[38:39], 0x800
	.p2alignl 6, 3212836864
; #define LAS __attribute__((address_space(3)))
; __device__ __forceinline__ void glds16(const void* gsrc, LAS unsigned char* dst_uniform) { __builtin_amdgcn_global_load_lds((const unsigned*)gsrc, (LAS unsigned*)dst_uniform, 16, 0, 0); }
; #define ATT_SYNC() do { asm volatile("s_waitcnt vmcnt(0) lgkmcnt(0)" ::: "memory"); __syncthreads(); } while (0)
; __device__ __forceinline__ void dil_unit(LAS unsigned char* lds, const LAS float* btab, const bf16_t* QKV, int gi, int ldil, int b, int h, int r, int ub, bf16_t* AO, float* lseacc, const int tid) {
;     ...
;     for (int ii = 0; ii < 12; ++ii) { const int i = wid * 12 + ii, kk = 4 * i + (lane >> 4), c = (lane & 15) ^ (kk & 15); int ki = k0 + kk; ki = ki < 0 ? 0 : (ki >= sub_len ? sub_len - 1 : ki);
;         glds16(base + (tokb + ((size_t)ki << ldil)) * 3072 + 1024 + c * 8, lds + i * 1024); }
;     const int qi = ub * 256 + wid * 32 + r32; const size_t qtok = tokb + ((size_t)qi << ldil);
;     bf16x8 qf[8]; { const bf16_t* qp = base + qtok * 3072 + hi * 8;
; #pragma unroll
;         for (int s = 0; s < 8; ++s) qf[s] = *(const bf16x8*)(qp + 16 * s); }
;     ATT_SYNC();
;     f32x16 S[5];
;     int r15 = r32 & 15; asm volatile("" : "+v"(r15));
; #pragma unroll
;     for (int t = 0; t < 5; ++t) { f32x16 acc = {}; const lds_cptr kp = (lds_cptr)lds + (32 * wid + 32 * t + r32) * 256;
; #pragma unroll
;         for (int s = 0; s < 8; ++s) { const bf16x8 kf = *(const LAS bf16x8*)(kp + (((2 * s + hi) ^ r15) << 4)); acc = __builtin_amdgcn_mfma_f32_32x32x16_bf16(kf, qf[s], acc, 0, 0, 0); }
; __global__ void __launch_bounds__(NWAVES * 64, 2) mk_fwd(Args a) {
;     ...
;                 if (tu < 192) { const int jk = tu - 32; btab[tu] = (jk >= 0 && jk <= 128) ? biasrel[(gi * 8 + h) * 129 + jk] : -1e30f; }
.LBB0_663:
	v_add_u32_e32 v10, s25, v2
	v_subrev_u32_e32 v0, 64, v10
	s_waitcnt lgkmcnt(0)
	v_min_i32_e32 v1, s18, v0
	v_cmp_lt_i32_e32 vcc, -1, v0
	v_add_u32_e32 v8, s25, v3
	v_xor_b32_e32 v9, v8, v237
	v_cndmask_b32_e32 v0, 0, v1, vcc
	v_ashrrev_i32_e32 v1, 31, v0
	v_lshlrev_b64 v[0:1], s12, v[0:1]
	v_lshl_add_u64 v[4:5], v[0:1], 0, s[0:1]
	v_mov_b64_e32 v[0:1], s[2:3]
	v_mad_u64_u32 v[6:7], s[30:31], v4, s36, v[0:1]
	v_mov_b32_e32 v4, v7
	v_mad_u64_u32 v[4:5], s[30:31], v5, s36, v[4:5]
	v_mov_b32_e32 v7, v4
	v_lshlrev_b32_e32 v4, 4, v9
	v_and_b32_e32 v208, 0xf0, v4
	v_lshl_add_u64 v[4:5], v[6:7], 0, v[208:209]
	v_lshl_add_u64 v[4:5], v[4:5], 0, s[38:39]
	s_mov_b32 m0, s28
	s_add_i32 s25, s25, 16
	global_load_lds_dwordx4 v[4:5], off
	v_add_u32_e32 v4, 4, v8
	v_xor_b32_e32 v9, v4, v237
	v_subrev_u32_e32 v4, 60, v10
	v_min_i32_e32 v5, s18, v4
	v_cmp_lt_i32_e32 vcc, -1, v4
	s_add_i32 m0, s28, 0x400
	s_nop 0
	v_cndmask_b32_e32 v4, 0, v5, vcc
	v_ashrrev_i32_e32 v5, 31, v4
	v_lshlrev_b64 v[4:5], s12, v[4:5]
	v_lshl_add_u64 v[4:5], v[4:5], 0, s[0:1]
	v_mad_u64_u32 v[6:7], s[30:31], v4, s36, v[0:1]
	v_mov_b32_e32 v4, v7
	v_mad_u64_u32 v[4:5], s[30:31], v5, s36, v[4:5]
	v_mov_b32_e32 v7, v4
	v_lshlrev_b32_e32 v4, 4, v9
	v_and_b32_e32 v208, 0xf0, v4
	v_lshl_add_u64 v[4:5], v[6:7], 0, v[208:209]
	v_lshl_add_u64 v[4:5], v[4:5], 0, s[38:39]
	global_load_lds_dwordx4 v[4:5], off
	v_add_u32_e32 v4, 8, v8
	v_xor_b32_e32 v9, v4, v237
	v_subrev_u32_e32 v4, 56, v10
	v_min_i32_e32 v5, s18, v4
	v_cmp_lt_i32_e32 vcc, -1, v4
	s_add_i32 m0, s28, 0x800
	s_nop 0
	v_cndmask_b32_e32 v4, 0, v5, vcc
	v_ashrrev_i32_e32 v5, 31, v4
	v_lshlrev_b64 v[4:5], s12, v[4:5]
	v_lshl_add_u64 v[4:5], v[4:5], 0, s[0:1]
	v_mad_u64_u32 v[6:7], s[30:31], v4, s36, v[0:1]
	v_mov_b32_e32 v4, v7
	v_mad_u64_u32 v[4:5], s[30:31], v5, s36, v[4:5]
	v_mov_b32_e32 v7, v4
	v_lshlrev_b32_e32 v4, 4, v9
	v_and_b32_e32 v208, 0xf0, v4
	v_lshl_add_u64 v[4:5], v[6:7], 0, v[208:209]
	v_lshl_add_u64 v[4:5], v[4:5], 0, s[38:39]
	global_load_lds_dwordx4 v[4:5], off
	v_add_u32_e32 v4, 12, v8
	v_xor_b32_e32 v6, v4, v237
	v_subrev_u32_e32 v4, 52, v10
	v_min_i32_e32 v5, s18, v4
	v_cmp_lt_i32_e32 vcc, -1, v4
	s_add_i32 m0, s28, 0xc00
	s_addk_i32 s28, 0x1000
	v_cndmask_b32_e32 v4, 0, v5, vcc
	v_ashrrev_i32_e32 v5, 31, v4
	v_lshlrev_b64 v[4:5], s12, v[4:5]
	v_lshl_add_u64 v[4:5], v[4:5], 0, s[0:1]
	v_mad_u64_u32 v[0:1], s[30:31], v4, s36, v[0:1]
	v_mov_b32_e32 v4, v1
	v_mad_u64_u32 v[4:5], s[30:31], v5, s36, v[4:5]
	v_mov_b32_e32 v1, v4
	v_lshlrev_b32_e32 v4, 4, v6
	v_and_b32_e32 v208, 0xf0, v4
	v_lshl_add_u64 v[0:1], v[0:1], 0, v[208:209]
	v_lshl_add_u64 v[0:1], v[0:1], 0, s[38:39]
	global_load_lds_dwordx4 v[0:1], off
	s_cmp_eq_u32 s25, 48
	s_cbranch_scc0 .LBB0_663
	s_lshl_b32 s28, s20, 5
	v_and_b32_e32 v240, 31, v237
	s_add_i32 s25, s28, s27
	v_or_b32_e32 v0, s25, v240
	v_ashrrev_i32_e32 v1, 31, v0
	v_lshlrev_b64 v[0:1], s12, v[0:1]
	v_lshl_add_u64 v[218:219], v[0:1], 0, s[0:1]
	v_mov_b64_e32 v[0:1], s[2:3]
	v_mad_u64_u32 v[0:1], s[30:31], v218, s36, v[0:1]
	v_mov_b32_e32 v2, v1
	v_lshrrev_b32_e32 v239, 5, v238
	v_mad_u64_u32 v[2:3], s[30:31], v219, s36, v[2:3]
	v_mov_b32_e32 v1, v2
	v_lshlrev_b32_e32 v220, 4, v239
	v_mov_b32_e32 v221, v209
	v_lshl_add_u64 v[4:5], v[0:1], 0, v[220:221]
	global_load_dwordx4 v[0:3], v[4:5], off
	global_load_dwordx4 v[80:83], v[4:5], off offset:32
	global_load_dwordx4 v[84:87], v[4:5], off offset:64
	global_load_dwordx4 v[88:91], v[4:5], off offset:96
	global_load_dwordx4 v[92:95], v[4:5], off offset:128
	global_load_dwordx4 v[96:99], v[4:5], off offset:160
	global_load_dwordx4 v[100:103], v[4:5], off offset:192
	global_load_dwordx4 v[104:107], v[4:5], off offset:224
	s_lshl_b32 s29, s20, 13
	v_and_b32_e32 v4, 15, v237
	s_add_i32 s29, s29, 0
	v_cmp_gt_i32_e32 vcc, 0xc0, v237
	s_nop 1
	s_and_saveexec_b64 vcc, vcc
	s_waitcnt vmcnt(0)
	ds_write_b32 v109, v108
	s_mov_b64 exec, vcc
	s_waitcnt vmcnt(0) lgkmcnt(0)
	s_waitcnt vmcnt(0) lgkmcnt(0)
	s_barrier
	v_lshl_add_u32 v6, v240, 8, s29
	v_xor_b32_e32 v5, v4, v239
	v_lshl_add_u32 v52, v5, 4, v6
	v_bitop3_b32 v5, v4, v239, 2 bitop3:0x1e
	v_lshl_add_u32 v53, v5, 4, v6
	v_bitop3_b32 v5, v4, v239, 4 bitop3:0x1e
	v_lshl_add_u32 v56, v5, 4, v6
	v_bitop3_b32 v5, v4, v239, 6 bitop3:0x1e
	v_lshl_add_u32 v57, v5, 4, v6
	v_bitop3_b32 v5, v4, v239, 8 bitop3:0x1e
	v_lshl_add_u32 v60, v5, 4, v6
	v_bitop3_b32 v5, v4, v239, 10 bitop3:0x1e
	v_lshl_add_u32 v61, v5, 4, v6
	v_bitop3_b32 v5, v4, v239, 12 bitop3:0x1e
	v_bitop3_b32 v4, v4, v239, 14 bitop3:0x1e
	v_lshl_add_u32 v65, v5, 4, v6
	v_lshl_add_u32 v66, v4, 4, v6
	ds_read_b128 v[24:27], v53
	ds_read_b128 v[4:7], v53 offset:8192
	ds_read_b128 v[32:35], v57
	ds_read_b128 v[8:11], v57 offset:8192
	ds_read_b128 v[36:39], v61
	ds_read_b128 v[12:15], v61 offset:8192
	ds_read_b128 v[40:43], v66
	ds_read_b128 v[16:19], v66 offset:8192
	ds_read_b128 v[44:47], v52 offset:8192
	ds_read_b128 v[20:23], v52 offset:16384
	ds_read_b128 v[128:131], v56 offset:8192
	ds_read_b128 v[28:31], v56 offset:16384
	ds_read_b128 v[136:139], v60 offset:8192
	ds_read_b128 v[108:111], v60 offset:16384
	ds_read_b128 v[144:147], v65 offset:8192
	ds_read_b128 v[112:115], v65 offset:16384
	ds_read_b128 v[148:151], v53 offset:16384
	ds_read_b128 v[116:119], v53 offset:24576
	ds_read_b128 v[160:163], v57 offset:16384
	ds_read_b128 v[120:123], v57 offset:24576
	ds_read_b128 v[168:171], v61 offset:16384
	ds_read_b128 v[124:127], v61 offset:24576
	ds_read_b128 v[176:179], v66 offset:16384
	ds_read_b128 v[132:135], v66 offset:24576
	ds_read_b128 v[48:51], v52
	ds_read_b128 v[140:143], v52 offset:32768
	ds_read_b128 v[192:195], v52 offset:24576
	ds_read_b128 v[152:155], v53 offset:32768
	ds_read_b128 v[52:55], v56
	ds_read_b128 v[156:159], v56 offset:32768
	ds_read_b128 v[196:199], v56 offset:24576
	ds_read_b128 v[164:167], v57 offset:32768
	ds_read_b128 v[56:59], v60
	ds_read_b128 v[172:175], v60 offset:32768
	ds_read_b128 v[200:203], v60 offset:24576
	ds_read_b128 v[180:183], v61 offset:32768
	ds_read_b128 v[60:63], v65
	ds_read_b128 v[184:187], v65 offset:32768
	ds_read_b128 v[204:207], v65 offset:24576
	ds_read_b128 v[188:191], v66 offset:32768
	s_sub_i32 s27, s27, 64
	v_lshlrev_b32_e32 v64, 3, v239
	s_waitcnt vmcnt(0) lgkmcnt(0)
	v_bfe_u32 v65, v237, 2, 3
	v_or3_b32 v64, v65, s27, v64
	v_lshlrev_b32_e32 v65, 3, v237
	v_lshrrev_b32_e32 v221, 2, v237
	v_and_b32_e32 v212, 24, v65
	s_mov_b32 s29, 0
	s_waitcnt lgkmcnt(0)
	s_barrier
	.p2alignl 6, 3212836864

;     __device__ __forceinline__ size_t hstep() const { return (size_t)HALF * K * 2; }
;     __device__ __forceinline__ const char* tile(const Unit& u, int t) const { return A + (size_t)u.pm * 2 * hstep() + (size_t)t * (BK * 2); }
;     __device__ __forceinline__ size_t hstep() const { return (size_t)HALF * 512; }
; #define PG8_STAGE(bufoff, gbase, voff) do { _Pragma("unroll") for (int _i = 0; _i < 2; ++_i) \
;         __builtin_amdgcn_global_load_lds((const unsigned*)((const char*)(gbase) + (voff)[_i]), (PG8_LAS unsigned*)(lds + (bufoff) + ldsw + _i * 8192), 16, 0, 0); } while (0)
; #define PG8_LDA(dst, b, h) do { _Pragma("unroll") for (int m = 0; m < 4; ++m) _Pragma("unroll") for (int k = 0; k < 2; ++k) dst[m][k] = *(const PG8_LAS bf16x8*)(lds + PG8_SA(b, h) + aoff + m * 2048 + k * 1024); } while (0)
; #define PG8_LDB(dst, b, h) do { _Pragma("unroll") for (int n = 0; n < 2; ++n) _Pragma("unroll") for (int k = 0; k < 2; ++k) dst[n][k] = *(const PG8_LAS bf16x8*)(lds + PG8_SB(b, h) + boff + n * 2048 + k * 1024); } while (0)
; #define PG8_WAIT_V(n) asm volatile("s_waitcnt vmcnt(" #n ")" ::: "memory")
; #define PG8_WAIT_L(n) asm volatile("s_waitcnt lgkmcnt(" #n ")" ::: "memory")
; #define PG8_BAR __builtin_amdgcn_s_barrier()
; #define PG8_SCHED __builtin_amdgcn_sched_barrier(0)
;     __device__ __forceinline__ const char* tile(const Unit& u, int t) const { return U + (long)(t >> 2) * xoff + (size_t)u.pn * (1024 * 512) + (size_t)u.pm * 2 * hstep() + (size_t)(t & 3) * (BK * 2); }
;     ...
;         for (int t = 0; t < nt; t += 2) {
;             const bool last = (t == nt - 2);
;             const char* a1 = AS.tile(cur, t + 1);
;             const char* a2 = last ? AS.tile(nu, 0) : AS.tile(cur, t + 2); const char* b2 = last ? nB : cB + (size_t)(t + 2) * kstep;
;             const char* a3 = last ? AS.tile(nu, 1) : AS.tile(cur, t + 3); const char* b3 = b2 + kstep;
;             PG8_LDB(B0, 0, 0); PG8_LDB(B1, 0, 1); PG8_SCHED; PG8_LDA(At, 0, 0); PG8_STAGE(PG8_SA(1, 1), a1 + hstepA, voffA);
;             PG8_WAIT_V(8); PG8_WAIT_L(0); PG8_BAR; PG8_MMA(0, 0, At, B0); PG8_MMA(0, 1, At, B1); PG8_BAR; PG8_SCHED;
;             PG8_LDA(At, 0, 1); PG8_STAGE(PG8_SB(0, 0), b2, voffB); PG8_STAGE(PG8_SB(0, 1), b2 + hstepB, voffB); PG8_STAGE(PG8_SA(0, 0), a2, voffA);
;             PG8_WAIT_V(8); PG8_WAIT_L(0); PG8_BAR; PG8_MMA(1, 0, At, B0); PG8_MMA(1, 1, At, B1); PG8_BAR; PG8_SCHED;
.LBB0_833:
	s_add_u32 s47, s44, s16
	s_addc_u32 s48, s45, s17
	s_and_b64 s[20:21], exec, s[20:21]
	s_cselect_b32 s21, s43, s48
	s_cselect_b32 s20, s42, s47
	s_add_i32 s47, s46, -3
	s_lshr_b32 s48, s47, 2
	s_mul_i32 s48, s48, 0x6000000
	s_add_u32 s48, s1, s48
	s_addc_u32 s49, s3, 0
	s_and_b32 s50, s16, 0x100
	s_add_u32 s48, s48, s50
	s_addc_u32 s49, s49, 0
	s_add_i32 s50, 0, 0x10000
	v_add_u32_e32 v137, s50, v144
	s_add_i32 s51, 0, 0x14000
	ds_read_b128 v[148:151], v137
	ds_read_b128 v[152:155], v137 offset:1024
	ds_read_b128 v[156:159], v137 offset:2048
	ds_read_b128 v[160:163], v137 offset:3072
	v_add_u32_e32 v137, s51, v144
	ds_read_b128 v[164:167], v137
	ds_read_b128 v[168:171], v137 offset:1024
	ds_read_b128 v[172:175], v137 offset:2048
	ds_read_b128 v[176:179], v137 offset:3072
	s_add_u32 s48, s48, 0x10080
	s_addc_u32 s49, s49, 0
	v_lshl_add_u64 v[140:141], s[48:49], 0, v[128:129]
	s_add_i32 m0, s27, 0xc000
	ds_read_b128 v[180:183], v142
	ds_read_b128 v[184:187], v142 offset:1024
	ds_read_b128 v[188:191], v142 offset:2048
	ds_read_b128 v[192:195], v142 offset:3072
	ds_read_b128 v[196:199], v142 offset:4096
	ds_read_b128 v[200:203], v142 offset:5120
	ds_read_b128 v[204:207], v142 offset:6144
	ds_read_b128 v[218:221], v142 offset:7168
	global_load_lds_dwordx4 v[140:141], off
	v_lshl_add_u64 v[140:141], s[48:49], 0, v[130:131]
	s_add_i32 m0, s27, 0xe000
	s_nop 0
	global_load_lds_dwordx4 v[140:141], off
	s_waitcnt vmcnt(8)
	s_waitcnt lgkmcnt(0)
	s_barrier
	s_setprio 1
	s_waitcnt lgkmcnt(0)
	v_mfma_f32_16x16x32_bf16 v[124:127], v[148:151], v[180:183], v[124:127]
	v_mfma_f32_16x16x32_bf16 v[120:123], v[156:159], v[180:183], v[120:123]
	v_mfma_f32_16x16x32_bf16 v[108:111], v[148:151], v[188:191], v[108:111]
	v_mfma_f32_16x16x32_bf16 v[104:107], v[156:159], v[188:191], v[104:107]
	v_mfma_f32_16x16x32_bf16 v[92:95], v[148:151], v[196:199], v[92:95]
	v_mfma_f32_16x16x32_bf16 v[88:91], v[156:159], v[196:199], v[88:91]
	v_mfma_f32_16x16x32_bf16 v[76:79], v[148:151], v[204:207], v[76:79]
	v_mfma_f32_16x16x32_bf16 v[72:75], v[156:159], v[204:207], v[72:75]
	v_mfma_f32_16x16x32_bf16 v[124:127], v[152:155], v[184:187], v[124:127]
	v_mfma_f32_16x16x32_bf16 v[120:123], v[160:163], v[184:187], v[120:123]
	v_mfma_f32_16x16x32_bf16 v[108:111], v[152:155], v[192:195], v[108:111]
	v_mfma_f32_16x16x32_bf16 v[104:107], v[160:163], v[192:195], v[104:107]
	v_mfma_f32_16x16x32_bf16 v[92:95], v[152:155], v[200:203], v[92:95]
	v_mfma_f32_16x16x32_bf16 v[88:91], v[160:163], v[200:203], v[88:91]
	v_mfma_f32_16x16x32_bf16 v[76:79], v[152:155], v[218:221], v[76:79]
	v_mfma_f32_16x16x32_bf16 v[72:75], v[160:163], v[218:221], v[72:75]
	s_setprio 0
	s_setprio 1
	v_mfma_f32_16x16x32_bf16 v[116:119], v[164:167], v[180:183], v[116:119]
	v_mfma_f32_16x16x32_bf16 v[112:115], v[172:175], v[180:183], v[112:115]
	v_mfma_f32_16x16x32_bf16 v[100:103], v[164:167], v[188:191], v[100:103]
	v_mfma_f32_16x16x32_bf16 v[96:99], v[172:175], v[188:191], v[96:99]
	v_mfma_f32_16x16x32_bf16 v[84:87], v[164:167], v[196:199], v[84:87]
	v_mfma_f32_16x16x32_bf16 v[80:83], v[172:175], v[196:199], v[80:83]
	v_mfma_f32_16x16x32_bf16 v[68:71], v[164:167], v[204:207], v[68:71]
	v_mfma_f32_16x16x32_bf16 v[64:67], v[172:175], v[204:207], v[64:67]
	v_mfma_f32_16x16x32_bf16 v[116:119], v[168:171], v[184:187], v[116:119]
	v_mfma_f32_16x16x32_bf16 v[112:115], v[176:179], v[184:187], v[112:115]
	v_mfma_f32_16x16x32_bf16 v[100:103], v[168:171], v[192:195], v[100:103]
	v_mfma_f32_16x16x32_bf16 v[96:99], v[176:179], v[192:195], v[96:99]
	v_mfma_f32_16x16x32_bf16 v[84:87], v[168:171], v[200:203], v[84:87]
	v_mfma_f32_16x16x32_bf16 v[80:83], v[176:179], v[200:203], v[80:83]
	v_mfma_f32_16x16x32_bf16 v[68:71], v[168:171], v[218:221], v[68:71]
	v_mfma_f32_16x16x32_bf16 v[64:67], v[176:179], v[218:221], v[64:67]
	s_setprio 0
	s_barrier
	s_add_i32 s48, s50, s26
	v_lshl_add_u64 v[140:141], s[20:21], 0, v[134:135]
	s_mov_b32 m0, s48
	ds_read_b128 v[180:183], v142 offset:16384
	ds_read_b128 v[184:187], v142 offset:17408
	ds_read_b128 v[188:191], v142 offset:18432
	ds_read_b128 v[192:195], v142 offset:19456
	ds_read_b128 v[196:199], v142 offset:20480
	ds_read_b128 v[200:203], v142 offset:21504
	ds_read_b128 v[204:207], v142 offset:22528
	ds_read_b128 v[218:221], v142 offset:23552
	global_load_lds_dwordx4 v[140:141], off
	s_add_i32 m0, s48, 0x2000
	s_add_u32 s48, s20, 0x20000
	v_lshl_add_u64 v[222:223], s[20:21], 0, v[132:133]
	s_addc_u32 s49, s21, 0
	s_add_i32 s50, s51, s26
	global_load_lds_dwordx4 v[222:223], off
	v_lshl_add_u64 v[224:225], s[48:49], 0, v[134:135]
	s_mov_b32 m0, s50
	s_nop 0
	global_load_lds_dwordx4 v[224:225], off
	v_lshl_add_u64 v[224:225], s[48:49], 0, v[132:133]
	s_add_i32 m0, s50, 0x2000
	s_nop 0
	global_load_lds_dwordx4 v[224:225], off
	v_lshl_add_u64 v[224:225], s[22:23], 0, v[128:129]
	s_mov_b32 m0, s27
	s_nop 0
	global_load_lds_dwordx4 v[224:225], off
	v_lshl_add_u64 v[224:225], s[22:23], 0, v[130:131]
	s_mov_b32 m0, s28
	s_nop 0
	global_load_lds_dwordx4 v[224:225], off
	s_waitcnt vmcnt(8)
	s_waitcnt lgkmcnt(0)
	s_barrier
; #define PG8_STAGE(bufoff, gbase, voff) do { _Pragma("unroll") for (int _i = 0; _i < 2; ++_i) \
;         __builtin_amdgcn_global_load_lds((const unsigned*)((const char*)(gbase) + (voff)[_i]), (PG8_LAS unsigned*)(lds + (bufoff) + ldsw + _i * 8192), 16, 0, 0); } while (0)
; #define PG8_LDA(dst, b, h) do { _Pragma("unroll") for (int m = 0; m < 4; ++m) _Pragma("unroll") for (int k = 0; k < 2; ++k) dst[m][k] = *(const PG8_LAS bf16x8*)(lds + PG8_SA(b, h) + aoff + m * 2048 + k * 1024); } while (0)
; #define PG8_LDB(dst, b, h) do { _Pragma("unroll") for (int n = 0; n < 2; ++n) _Pragma("unroll") for (int k = 0; k < 2; ++k) dst[n][k] = *(const PG8_LAS bf16x8*)(lds + PG8_SB(b, h) + boff + n * 2048 + k * 1024); } while (0)
; #define PG8_MMA(ai, bj, At, Bt) do { __builtin_amdgcn_s_setprio(1); _Pragma("unroll") for (int m = 0; m < 4; ++m) _Pragma("unroll") for (int n = 0; n < 2; ++n) _Pragma("unroll") for (int k = 0; k < 2; ++k) \
;         acc[ai][bj][m][n] = __builtin_amdgcn_mfma_f32_16x16x32_bf16(Bt[n][k], At[m][k], acc[ai][bj][m][n], 0, 0, 0); __builtin_amdgcn_s_setprio(0); } while (0)
; #define PG8_WAIT_V(n) asm volatile("s_waitcnt vmcnt(" #n ")" ::: "memory")
; #define PG8_WAIT_L(n) asm volatile("s_waitcnt lgkmcnt(" #n ")" ::: "memory")
; #define PG8_BAR __builtin_amdgcn_s_barrier()
; #define PG8_SCHED __builtin_amdgcn_sched_barrier(0)
;     ...
;             PG8_WAIT_V(8); PG8_WAIT_L(0); PG8_BAR; PG8_MMA(1, 0, At, B0); PG8_MMA(1, 1, At, B1); PG8_BAR; PG8_SCHED;
;             PG8_LDB(B0, 1, 0); PG8_LDB(B1, 1, 1); PG8_SCHED; PG8_LDA(At, 1, 0); PG8_STAGE(PG8_SA(0, 1), a2 + hstepA, voffA);
;             PG8_WAIT_V(8); PG8_WAIT_L(0); PG8_BAR; PG8_MMA(0, 0, At, B0); PG8_MMA(0, 1, At, B1); PG8_BAR; PG8_SCHED;
	s_setprio 1
	s_waitcnt lgkmcnt(0)
	v_mfma_f32_16x16x32_bf16 v[60:63], v[148:151], v[180:183], v[60:63]
	v_mfma_f32_16x16x32_bf16 v[56:59], v[156:159], v[180:183], v[56:59]
	v_mfma_f32_16x16x32_bf16 v[44:47], v[148:151], v[188:191], v[44:47]
	v_mfma_f32_16x16x32_bf16 v[40:43], v[156:159], v[188:191], v[40:43]
	v_mfma_f32_16x16x32_bf16 v[28:31], v[148:151], v[196:199], v[28:31]
	v_mfma_f32_16x16x32_bf16 v[24:27], v[156:159], v[196:199], v[24:27]
	v_mfma_f32_16x16x32_bf16 v[12:15], v[148:151], v[204:207], v[12:15]
	v_mfma_f32_16x16x32_bf16 v[8:11], v[156:159], v[204:207], v[8:11]
	v_mfma_f32_16x16x32_bf16 v[60:63], v[152:155], v[184:187], v[60:63]
	v_mfma_f32_16x16x32_bf16 v[56:59], v[160:163], v[184:187], v[56:59]
	v_mfma_f32_16x16x32_bf16 v[44:47], v[152:155], v[192:195], v[44:47]
	v_mfma_f32_16x16x32_bf16 v[40:43], v[160:163], v[192:195], v[40:43]
	v_mfma_f32_16x16x32_bf16 v[28:31], v[152:155], v[200:203], v[28:31]
	v_mfma_f32_16x16x32_bf16 v[24:27], v[160:163], v[200:203], v[24:27]
	v_mfma_f32_16x16x32_bf16 v[12:15], v[152:155], v[218:221], v[12:15]
	v_mfma_f32_16x16x32_bf16 v[8:11], v[160:163], v[218:221], v[8:11]
	s_setprio 0
	s_setprio 1
	v_mfma_f32_16x16x32_bf16 v[52:55], v[164:167], v[180:183], v[52:55]
	v_mfma_f32_16x16x32_bf16 v[48:51], v[172:175], v[180:183], v[48:51]
	v_mfma_f32_16x16x32_bf16 v[36:39], v[164:167], v[188:191], v[36:39]
	v_mfma_f32_16x16x32_bf16 v[32:35], v[172:175], v[188:191], v[32:35]
	v_mfma_f32_16x16x32_bf16 v[20:23], v[164:167], v[196:199], v[20:23]
	v_mfma_f32_16x16x32_bf16 v[16:19], v[172:175], v[196:199], v[16:19]
	v_mfma_f32_16x16x32_bf16 v[4:7], v[164:167], v[204:207], v[4:7]
	v_mfma_f32_16x16x32_bf16 v[0:3], v[172:175], v[204:207], v[0:3]
	v_mfma_f32_16x16x32_bf16 v[52:55], v[168:171], v[184:187], v[52:55]
	v_mfma_f32_16x16x32_bf16 v[48:51], v[176:179], v[184:187], v[48:51]
	v_mfma_f32_16x16x32_bf16 v[36:39], v[168:171], v[192:195], v[36:39]
	v_mfma_f32_16x16x32_bf16 v[32:35], v[176:179], v[192:195], v[32:35]
	v_mfma_f32_16x16x32_bf16 v[20:23], v[168:171], v[200:203], v[20:23]
	v_mfma_f32_16x16x32_bf16 v[16:19], v[176:179], v[200:203], v[16:19]
	v_mfma_f32_16x16x32_bf16 v[4:7], v[168:171], v[218:221], v[4:7]
	v_mfma_f32_16x16x32_bf16 v[0:3], v[176:179], v[218:221], v[0:3]
	s_setprio 0
	s_barrier
	s_add_i32 s48, 0, 0x18000
	v_add_u32_e32 v137, s48, v144
	s_add_i32 s49, 0, 0x1c000
	ds_read_b128 v[148:151], v137
	ds_read_b128 v[152:155], v137 offset:1024
	ds_read_b128 v[156:159], v137 offset:2048
	ds_read_b128 v[160:163], v137 offset:3072
	v_add_u32_e32 v137, s49, v144
	ds_read_b128 v[164:167], v137
	ds_read_b128 v[168:171], v137 offset:1024
	ds_read_b128 v[172:175], v137 offset:2048
	ds_read_b128 v[176:179], v137 offset:3072
	s_add_u32 s22, s22, 0x10000
	s_addc_u32 s23, s23, 0
	s_mov_b32 m0, s29
	v_lshl_add_u64 v[224:225], s[22:23], 0, v[128:129]
	ds_read_b128 v[180:183], v142 offset:32768
	ds_read_b128 v[184:187], v142 offset:33792
	ds_read_b128 v[188:191], v142 offset:34816
	ds_read_b128 v[192:195], v142 offset:35840
	ds_read_b128 v[196:199], v142 offset:36864
	ds_read_b128 v[200:203], v142 offset:37888
	ds_read_b128 v[204:207], v142 offset:38912
	ds_read_b128 v[218:221], v142 offset:39936
	global_load_lds_dwordx4 v[224:225], off
	v_lshl_add_u64 v[224:225], s[22:23], 0, v[130:131]
	s_mov_b32 m0, s30
	s_nop 0
	global_load_lds_dwordx4 v[224:225], off
	s_waitcnt vmcnt(8)
	s_waitcnt lgkmcnt(0)
	s_barrier
	s_setprio 1
	s_waitcnt lgkmcnt(0)
	v_mfma_f32_16x16x32_bf16 v[124:127], v[148:151], v[180:183], v[124:127]
	v_mfma_f32_16x16x32_bf16 v[120:123], v[156:159], v[180:183], v[120:123]
	v_mfma_f32_16x16x32_bf16 v[108:111], v[148:151], v[188:191], v[108:111]
	v_mfma_f32_16x16x32_bf16 v[104:107], v[156:159], v[188:191], v[104:107]
	v_mfma_f32_16x16x32_bf16 v[92:95], v[148:151], v[196:199], v[92:95]
	v_mfma_f32_16x16x32_bf16 v[88:91], v[156:159], v[196:199], v[88:91]
	v_mfma_f32_16x16x32_bf16 v[76:79], v[148:151], v[204:207], v[76:79]
	v_mfma_f32_16x16x32_bf16 v[72:75], v[156:159], v[204:207], v[72:75]
	v_mfma_f32_16x16x32_bf16 v[124:127], v[152:155], v[184:187], v[124:127]
	v_mfma_f32_16x16x32_bf16 v[120:123], v[160:163], v[184:187], v[120:123]
	v_mfma_f32_16x16x32_bf16 v[108:111], v[152:155], v[192:195], v[108:111]
	v_mfma_f32_16x16x32_bf16 v[104:107], v[160:163], v[192:195], v[104:107]
	v_mfma_f32_16x16x32_bf16 v[92:95], v[152:155], v[200:203], v[92:95]
	v_mfma_f32_16x16x32_bf16 v[88:91], v[160:163], v[200:203], v[88:91]
	v_mfma_f32_16x16x32_bf16 v[76:79], v[152:155], v[218:221], v[76:79]
	v_mfma_f32_16x16x32_bf16 v[72:75], v[160:163], v[218:221], v[72:75]
	s_setprio 0
	s_setprio 1
	v_mfma_f32_16x16x32_bf16 v[116:119], v[164:167], v[180:183], v[116:119]
	v_mfma_f32_16x16x32_bf16 v[112:115], v[172:175], v[180:183], v[112:115]
	v_mfma_f32_16x16x32_bf16 v[100:103], v[164:167], v[188:191], v[100:103]
	v_mfma_f32_16x16x32_bf16 v[96:99], v[172:175], v[188:191], v[96:99]
	v_mfma_f32_16x16x32_bf16 v[84:87], v[164:167], v[196:199], v[84:87]
	v_mfma_f32_16x16x32_bf16 v[80:83], v[172:175], v[196:199], v[80:83]
	v_mfma_f32_16x16x32_bf16 v[68:71], v[164:167], v[204:207], v[68:71]
	v_mfma_f32_16x16x32_bf16 v[64:67], v[172:175], v[204:207], v[64:67]
	v_mfma_f32_16x16x32_bf16 v[116:119], v[168:171], v[184:187], v[116:119]
	v_mfma_f32_16x16x32_bf16 v[112:115], v[176:179], v[184:187], v[112:115]
	v_mfma_f32_16x16x32_bf16 v[100:103], v[168:171], v[192:195], v[100:103]
	v_mfma_f32_16x16x32_bf16 v[96:99], v[176:179], v[192:195], v[96:99]
	v_mfma_f32_16x16x32_bf16 v[84:87], v[168:171], v[200:203], v[84:87]
	v_mfma_f32_16x16x32_bf16 v[80:83], v[176:179], v[200:203], v[80:83]
	v_mfma_f32_16x16x32_bf16 v[68:71], v[168:171], v[218:221], v[68:71]
	v_mfma_f32_16x16x32_bf16 v[64:67], v[176:179], v[218:221], v[64:67]
	s_setprio 0
	s_barrier
; #define PG8_STAGE(bufoff, gbase, voff) do { _Pragma("unroll") for (int _i = 0; _i < 2; ++_i) \
;         __builtin_amdgcn_global_load_lds((const unsigned*)((const char*)(gbase) + (voff)[_i]), (PG8_LAS unsigned*)(lds + (bufoff) + ldsw + _i * 8192), 16, 0, 0); } while (0)
; #define PG8_LDA(dst, b, h) do { _Pragma("unroll") for (int m = 0; m < 4; ++m) _Pragma("unroll") for (int k = 0; k < 2; ++k) dst[m][k] = *(const PG8_LAS bf16x8*)(lds + PG8_SA(b, h) + aoff + m * 2048 + k * 1024); } while (0)
; #define PG8_MMA(ai, bj, At, Bt) do { __builtin_amdgcn_s_setprio(1); _Pragma("unroll") for (int m = 0; m < 4; ++m) _Pragma("unroll") for (int n = 0; n < 2; ++n) _Pragma("unroll") for (int k = 0; k < 2; ++k) \
;         acc[ai][bj][m][n] = __builtin_amdgcn_mfma_f32_16x16x32_bf16(Bt[n][k], At[m][k], acc[ai][bj][m][n], 0, 0, 0); __builtin_amdgcn_s_setprio(0); } while (0)
; #define PG8_WAIT_V(n) asm volatile("s_waitcnt vmcnt(" #n ")" ::: "memory")
; #define PG8_WAIT_L(n) asm volatile("s_waitcnt lgkmcnt(" #n ")" ::: "memory")
; #define PG8_BAR __builtin_amdgcn_s_barrier()
; #define PG8_SCHED __builtin_amdgcn_sched_barrier(0)
;     ...
;         for (int t = 0; t < nt; t += 2) {
;     ...
;             PG8_LDA(At, 1, 1); PG8_STAGE(PG8_SB(1, 0), b3, voffB); PG8_STAGE(PG8_SB(1, 1), b3 + hstepB, voffB); PG8_STAGE(PG8_SA(1, 0), a3, voffA);
;             PG8_WAIT_V(8); PG8_WAIT_L(0); PG8_BAR; PG8_MMA(1, 0, At, B0); PG8_MMA(1, 1, At, B1); PG8_BAR; PG8_SCHED;
	s_mov_b64 s[50:51], 0x80
	s_add_i32 s22, s48, s26
	v_lshl_add_u64 v[140:141], v[140:141], 0, s[50:51]
	s_mov_b32 m0, s22
	ds_read_b128 v[180:183], v142 offset:49152
	ds_read_b128 v[184:187], v142 offset:50176
	ds_read_b128 v[188:191], v142 offset:51200
	ds_read_b128 v[192:195], v142 offset:52224
	ds_read_b128 v[196:199], v142 offset:53248
	ds_read_b128 v[200:203], v142 offset:54272
	ds_read_b128 v[204:207], v142 offset:55296
	ds_read_b128 v[218:221], v142 offset:56320
	global_load_lds_dwordx4 v[140:141], off
	s_add_i32 m0, s22, 0x2000
	s_add_u32 s20, s20, 0x20080
	v_lshl_add_u64 v[140:141], v[222:223], 0, s[50:51]
	s_addc_u32 s21, s21, 0
	s_add_i32 s22, s49, s26
	global_load_lds_dwordx4 v[140:141], off
	v_lshl_add_u64 v[140:141], s[20:21], 0, v[134:135]
	s_mov_b32 m0, s22
	s_nop 0
	global_load_lds_dwordx4 v[140:141], off
	v_lshl_add_u64 v[140:141], s[20:21], 0, v[132:133]
	s_add_i32 m0, s22, 0x2000
	s_nop 0
	global_load_lds_dwordx4 v[140:141], off
	v_lshl_add_u64 v[140:141], s[18:19], 0, v[128:129]
	s_mov_b32 m0, s31
	s_nop 0
	global_load_lds_dwordx4 v[140:141], off
	v_lshl_add_u64 v[140:141], s[18:19], 0, v[130:131]
	s_mov_b32 m0, s34
	s_nop 0
	global_load_lds_dwordx4 v[140:141], off
	s_waitcnt vmcnt(8)
	s_waitcnt lgkmcnt(0)
	s_barrier
	s_setprio 1
	s_waitcnt lgkmcnt(0)
	v_mfma_f32_16x16x32_bf16 v[60:63], v[148:151], v[180:183], v[60:63]
	v_mfma_f32_16x16x32_bf16 v[56:59], v[156:159], v[180:183], v[56:59]
	v_mfma_f32_16x16x32_bf16 v[44:47], v[148:151], v[188:191], v[44:47]
	v_mfma_f32_16x16x32_bf16 v[40:43], v[156:159], v[188:191], v[40:43]
	v_mfma_f32_16x16x32_bf16 v[28:31], v[148:151], v[196:199], v[28:31]
	v_mfma_f32_16x16x32_bf16 v[24:27], v[156:159], v[196:199], v[24:27]
	v_mfma_f32_16x16x32_bf16 v[12:15], v[148:151], v[204:207], v[12:15]
	v_mfma_f32_16x16x32_bf16 v[8:11], v[156:159], v[204:207], v[8:11]
	v_mfma_f32_16x16x32_bf16 v[60:63], v[152:155], v[184:187], v[60:63]
	v_mfma_f32_16x16x32_bf16 v[56:59], v[160:163], v[184:187], v[56:59]
	v_mfma_f32_16x16x32_bf16 v[44:47], v[152:155], v[192:195], v[44:47]
	v_mfma_f32_16x16x32_bf16 v[40:43], v[160:163], v[192:195], v[40:43]
	v_mfma_f32_16x16x32_bf16 v[28:31], v[152:155], v[200:203], v[28:31]
	v_mfma_f32_16x16x32_bf16 v[24:27], v[160:163], v[200:203], v[24:27]
	v_mfma_f32_16x16x32_bf16 v[12:15], v[152:155], v[218:221], v[12:15]
	v_mfma_f32_16x16x32_bf16 v[8:11], v[160:163], v[218:221], v[8:11]
	s_setprio 0
	s_setprio 1
	v_mfma_f32_16x16x32_bf16 v[52:55], v[164:167], v[180:183], v[52:55]
	v_mfma_f32_16x16x32_bf16 v[48:51], v[172:175], v[180:183], v[48:51]
	v_mfma_f32_16x16x32_bf16 v[36:39], v[164:167], v[188:191], v[36:39]
	v_mfma_f32_16x16x32_bf16 v[32:35], v[172:175], v[188:191], v[32:35]
	v_mfma_f32_16x16x32_bf16 v[20:23], v[164:167], v[196:199], v[20:23]
	v_mfma_f32_16x16x32_bf16 v[16:19], v[172:175], v[196:199], v[16:19]
	v_mfma_f32_16x16x32_bf16 v[4:7], v[164:167], v[204:207], v[4:7]
	v_mfma_f32_16x16x32_bf16 v[0:3], v[172:175], v[204:207], v[0:3]
	v_mfma_f32_16x16x32_bf16 v[52:55], v[168:171], v[184:187], v[52:55]
	v_mfma_f32_16x16x32_bf16 v[48:51], v[176:179], v[184:187], v[48:51]
	v_mfma_f32_16x16x32_bf16 v[36:39], v[168:171], v[192:195], v[36:39]
	v_mfma_f32_16x16x32_bf16 v[32:35], v[176:179], v[192:195], v[32:35]
	v_mfma_f32_16x16x32_bf16 v[20:23], v[168:171], v[200:203], v[20:23]
	v_mfma_f32_16x16x32_bf16 v[16:19], v[176:179], v[200:203], v[16:19]
	v_mfma_f32_16x16x32_bf16 v[4:7], v[168:171], v[218:221], v[4:7]
	v_mfma_f32_16x16x32_bf16 v[0:3], v[176:179], v[218:221], v[0:3]
	s_setprio 0
	s_barrier
	s_add_u32 s16, s16, 0x100
	s_addc_u32 s17, s17, 0
	s_add_i32 s46, s46, 2
	s_cmp_gt_u32 s47, 5
	s_cbranch_scc1 .LBB0_838
	.p2alignl 6, 3212836864
